# attention matrix segment: QK MFMAs issued before the PV MFMAs
# baseline (speedup 1.0000x reference)
.Lattn_tb2:
	ds_read_b128 v[216:219], v182 offset:32768
	ds_read_b128 v[220:223], v182 offset:36864
	ds_read_b128 v[224:227], v183 offset:32768
	ds_read_b128 v[228:231], v183 offset:36864
	ds_read_b128 v[208:211], v184 offset:32768
	ds_read_b128 v[212:215], v184 offset:36864
	v_max3_f32 v254, v64, v65, v66
	s_add_i32 m0, s5, 0
	v_max3_f32 v255, v80, v81, v82
	global_load_lds_dwordx4 v170, s[48:49]
	v_max3_f32 v254, v254, v67, v68
	s_add_i32 m0, s5, 8192
	v_max3_f32 v255, v255, v83, v84
	global_load_lds_dwordx4 v170, s[50:51]
	v_max3_f32 v254, v254, v69, v70
	s_add_i32 m0, s5, 98304
	v_max3_f32 v255, v255, v85, v86
	global_load_lds_dwordx4 v172, s[52:53]
	v_max3_f32 v254, v254, v71, v72
	s_add_i32 m0, s5, 106496
	v_max3_f32 v255, v255, v87, v88
	global_load_lds_dwordx4 v172, s[54:55]
	v_max3_f32 v254, v254, v73, v74
	v_max3_f32 v255, v255, v89, v90
	v_max3_f32 v254, v254, v75, v76
	v_max3_f32 v255, v255, v91, v92
	v_max3_f32 v254, v254, v77, v78
	v_max3_f32 v255, v255, v93, v94
	v_max3_f32 v254, v254, v79, v95
	v_max_f32_e32 v254, v254, v255
	v_mov_b32_e32 v180, 0xc2800000
	v_cmp_lt_f32_e32 vcc, 0x4138aa3b, v254
	v_cmp_gt_f32_e64 s[40:41], v180, v254
	s_nop 4
	s_or_b64 vcc, vcc, s[40:41]
	s_nop 0
	s_cbranch_vccnz .Lattn_sp_t0
	v_exp_f32_e32 v64, v64
	v_exp_f32_e32 v65, v65
	v_exp_f32_e32 v66, v66
	v_exp_f32_e32 v67, v67
	v_exp_f32_e32 v68, v68
	v_exp_f32_e32 v69, v69
	v_exp_f32_e32 v70, v70
	v_exp_f32_e32 v71, v71
	v_add_f32_e32 v190, v64, v65
	v_add_f32_e32 v191, v66, v67
	v_add_f32_e32 v190, v190, v68
	v_add_f32_e32 v191, v191, v69
	v_add_f32_e32 v190, v190, v70
	v_add_f32_e32 v191, v191, v71
	v_cvt_pk_bf16_f32 v144, v64, v65
	v_cvt_pk_bf16_f32 v145, v66, v67
	v_cvt_pk_bf16_f32 v146, v68, v69
	v_cvt_pk_bf16_f32 v147, v70, v71
	v_exp_f32_e32 v72, v72
	v_exp_f32_e32 v73, v73
	v_exp_f32_e32 v74, v74
	v_exp_f32_e32 v75, v75
	v_exp_f32_e32 v76, v76
	v_exp_f32_e32 v77, v77
	v_exp_f32_e32 v78, v78
	v_exp_f32_e32 v79, v79
	v_add_f32_e32 v190, v190, v72
	v_add_f32_e32 v191, v191, v73
	v_add_f32_e32 v190, v190, v74
	v_add_f32_e32 v191, v191, v75
	v_add_f32_e32 v190, v190, v76
	v_add_f32_e32 v191, v191, v77
	v_add_f32_e32 v190, v190, v78
	v_add_f32_e32 v191, v191, v79
	v_cvt_pk_bf16_f32 v148, v72, v73
	v_cvt_pk_bf16_f32 v149, v74, v75
	v_cvt_pk_bf16_f32 v150, v76, v77
	v_cvt_pk_bf16_f32 v151, v78, v79
	v_exp_f32_e32 v80, v80
	v_exp_f32_e32 v81, v81
	v_exp_f32_e32 v82, v82
	v_exp_f32_e32 v83, v83
	v_exp_f32_e32 v84, v84
	v_exp_f32_e32 v85, v85
	v_exp_f32_e32 v86, v86
	v_exp_f32_e32 v87, v87
	v_add_f32_e32 v190, v190, v80
	v_add_f32_e32 v191, v191, v81
	v_add_f32_e32 v190, v190, v82
	v_add_f32_e32 v191, v191, v83
	v_add_f32_e32 v190, v190, v84
	v_add_f32_e32 v191, v191, v85
	v_add_f32_e32 v190, v190, v86
	v_add_f32_e32 v191, v191, v87
	v_cvt_pk_bf16_f32 v152, v80, v81
	v_cvt_pk_bf16_f32 v153, v82, v83
	v_cvt_pk_bf16_f32 v154, v84, v85
	v_cvt_pk_bf16_f32 v155, v86, v87
	v_exp_f32_e32 v88, v88
	v_exp_f32_e32 v89, v89
	v_exp_f32_e32 v90, v90
	v_exp_f32_e32 v91, v91
	v_exp_f32_e32 v92, v92
	v_exp_f32_e32 v93, v93
	v_exp_f32_e32 v94, v94
	v_exp_f32_e32 v95, v95
	v_add_f32_e32 v190, v190, v88
	v_add_f32_e32 v191, v191, v89
	v_add_f32_e32 v190, v190, v90
	v_add_f32_e32 v191, v191, v91
	v_add_f32_e32 v190, v190, v92
	v_add_f32_e32 v191, v191, v93
	v_add_f32_e32 v190, v190, v94
	v_add_f32_e32 v191, v191, v95
	v_cvt_pk_bf16_f32 v156, v88, v89
	v_cvt_pk_bf16_f32 v157, v90, v91
	v_cvt_pk_bf16_f32 v158, v92, v93
	v_cvt_pk_bf16_f32 v159, v94, v95
	v_add_f32_e32 v190, v190, v191
	v_add_f32_e32 v167, v167, v190
	s_add_i32 s42, s31, 1
	s_movk_i32 s47, 7

.Lattn_tb3:
	s_waitcnt lgkmcnt(5)
	v_mfma_f32_32x32x16_bf16 v[64:79], v[216:219], v[128:131], 0
	ds_read_b128 v[216:219], v185 offset:32768
	s_add_i32 s2, s42, 4
	s_waitcnt lgkmcnt(5)
	v_mfma_f32_32x32x16_bf16 v[80:95], v[220:223], v[128:131], 0
	ds_read_b128 v[220:223], v185 offset:36864
	s_and_b32 s2, s2, 31
	s_waitcnt lgkmcnt(5)
	v_mfma_f32_32x32x16_bf16 v[64:79], v[224:227], v[132:135], v[64:79]
	ds_read_b128 v[224:227], v187 offset:0
	s_mul_i32 s2, s2, 0x44000
	s_waitcnt lgkmcnt(5)
	v_mfma_f32_32x32x16_bf16 v[80:95], v[228:231], v[132:135], v[80:95]
	ds_read_b128 v[228:231], v187 offset:4096
	s_add_u32 s48, s26, s2
	s_waitcnt lgkmcnt(5)
	v_mfma_f32_32x32x16_bf16 v[64:79], v[208:211], v[136:139], v[64:79]
	ds_read_b128 v[208:211], v187 offset:8192
	s_addc_u32 s49, s27, 0
	s_waitcnt lgkmcnt(5)
	v_mfma_f32_32x32x16_bf16 v[80:95], v[212:215], v[136:139], v[80:95]
	ds_read_b128 v[212:215], v187 offset:12288
	s_add_u32 s50, s48, 0x80
	s_waitcnt lgkmcnt(5)
	v_mfma_f32_32x32x16_bf16 v[64:79], v[216:219], v[140:143], v[64:79]
	ds_read_b128 v[216:219], v188 offset:0
	s_addc_u32 s51, s49, 0
	s_waitcnt lgkmcnt(5)
	v_mfma_f32_32x32x16_bf16 v[80:95], v[220:223], v[140:143], v[80:95]
	ds_read_b128 v[220:223], v188 offset:4096
	s_add_i32 s2, s42, 2
	s_waitcnt lgkmcnt(5)
	v_mfma_f32_32x32x16_bf16 v[48:63], v[224:227], v[144:147], v[48:63]
	ds_read_b128 v[224:227], v188 offset:8192
	s_and_b32 s2, s2, 31
	s_waitcnt lgkmcnt(5)
	v_mfma_f32_32x32x16_bf16 v[32:47], v[228:231], v[144:147], v[32:47]
	ds_read_b128 v[228:231], v188 offset:12288
	s_lshl_b32 s2, s2, 7
	s_waitcnt lgkmcnt(5)
	v_mfma_f32_32x32x16_bf16 v[16:31], v[208:211], v[144:147], v[16:31]
	ds_read_b128 v[208:211], v186 offset:0
	s_add_u32 s52, s10, s2
	s_waitcnt lgkmcnt(5)
	v_mfma_f32_32x32x16_bf16 v[0:15], v[212:215], v[144:147], v[0:15]
	ds_read_b128 v[212:215], v186 offset:4096
	s_addc_u32 s53, s11, 0
	s_waitcnt lgkmcnt(5)
	v_mfma_f32_32x32x16_bf16 v[48:63], v[216:219], v[148:151], v[48:63]
	ds_read_b128 v[216:219], v186 offset:8192
	s_add_u32 s54, s52, 0x204000
	s_waitcnt lgkmcnt(5)
	v_mfma_f32_32x32x16_bf16 v[32:47], v[220:223], v[148:151], v[32:47]
	ds_read_b128 v[220:223], v186 offset:12288
	s_addc_u32 s55, s53, 0
	s_waitcnt lgkmcnt(5)
	v_mfma_f32_32x32x16_bf16 v[16:31], v[224:227], v[148:151], v[16:31]
	ds_read_b128 v[224:227], v189 offset:0
	s_waitcnt lgkmcnt(5)
	v_mfma_f32_32x32x16_bf16 v[0:15], v[228:231], v[148:151], v[0:15]
	ds_read_b128 v[228:231], v189 offset:4096
	s_waitcnt lgkmcnt(5)
	v_mfma_f32_32x32x16_bf16 v[48:63], v[208:211], v[152:155], v[48:63]
	ds_read_b128 v[208:211], v189 offset:8192
	s_waitcnt lgkmcnt(5)
	v_mfma_f32_32x32x16_bf16 v[32:47], v[212:215], v[152:155], v[32:47]
	ds_read_b128 v[212:215], v189 offset:12288
	s_waitcnt lgkmcnt(5)
	v_mfma_f32_32x32x16_bf16 v[16:31], v[216:219], v[152:155], v[16:31]
	s_waitcnt lgkmcnt(4)
	v_mfma_f32_32x32x16_bf16 v[0:15], v[220:223], v[152:155], v[0:15]
	s_waitcnt lgkmcnt(3)
	v_mfma_f32_32x32x16_bf16 v[48:63], v[224:227], v[156:159], v[48:63]
	s_waitcnt lgkmcnt(2)
	v_mfma_f32_32x32x16_bf16 v[32:47], v[228:231], v[156:159], v[32:47]
	s_waitcnt lgkmcnt(1)
	v_mfma_f32_32x32x16_bf16 v[16:31], v[208:211], v[156:159], v[16:31]
	s_waitcnt lgkmcnt(0)
	v_mfma_f32_32x32x16_bf16 v[0:15], v[212:215], v[156:159], v[0:15]
	s_cmp_lg_u32 s14, 0
	s_cbranch_scc0 .Lattn_tb4
	s_waitcnt vmcnt(4)
	s_barrier
.Lattn_tb4:
	ds_read_b128 v[216:219], v182 offset:49152
	ds_read_b128 v[220:223], v182 offset:53248
	ds_read_b128 v[224:227], v183 offset:49152
	ds_read_b128 v[228:231], v183 offset:53248
	ds_read_b128 v[208:211], v184 offset:49152
	ds_read_b128 v[212:215], v184 offset:53248
	v_exp_f32_e32 v171, v96
	v_exp_f32_e32 v173, v97
	v_exp_f32_e32 v179, v98
	s_add_i32 m0, s5, 16384
	v_exp_f32_e32 v180, v99
	v_exp_f32_e32 v232, v100
	v_exp_f32_e32 v233, v101
	global_load_lds_dwordx4 v170, s[48:49]
	v_exp_f32_e32 v234, v102
	v_exp_f32_e32 v235, v103
	v_add_f32_e32 v190, v171, v173
	s_add_i32 m0, s5, 24576
	v_add_f32_e32 v191, v179, v180
	v_add_f32_e32 v190, v190, v232
	v_add_f32_e32 v191, v191, v233
	global_load_lds_dwordx4 v170, s[50:51]
	v_add_f32_e32 v190, v190, v234
	v_add_f32_e32 v191, v191, v235
	v_cvt_pk_bf16_f32 v144, v171, v173
	s_add_i32 m0, s5, 114688
	v_cvt_pk_bf16_f32 v145, v179, v180
	v_cvt_pk_bf16_f32 v146, v232, v233
	v_cvt_pk_bf16_f32 v147, v234, v235
	global_load_lds_dwordx4 v172, s[52:53]
	v_exp_f32_e32 v171, v104
	v_exp_f32_e32 v173, v105
	v_exp_f32_e32 v179, v106
	s_add_i32 m0, s5, 122880
	v_exp_f32_e32 v180, v107
	v_exp_f32_e32 v232, v108
	v_exp_f32_e32 v233, v109
	global_load_lds_dwordx4 v172, s[54:55]
	v_exp_f32_e32 v234, v110
	v_exp_f32_e32 v235, v111
	v_add_f32_e32 v190, v190, v171
	v_add_f32_e32 v191, v191, v173
	v_add_f32_e32 v190, v190, v179
	v_add_f32_e32 v191, v191, v180
	v_add_f32_e32 v190, v190, v232
	v_add_f32_e32 v191, v191, v233
	v_add_f32_e32 v190, v190, v234
	v_add_f32_e32 v191, v191, v235
	v_cvt_pk_bf16_f32 v148, v171, v173
	v_cvt_pk_bf16_f32 v149, v179, v180
	v_cvt_pk_bf16_f32 v150, v232, v233
	v_cvt_pk_bf16_f32 v151, v234, v235
	v_exp_f32_e32 v171, v112
	v_exp_f32_e32 v173, v113
	v_exp_f32_e32 v179, v114
	v_exp_f32_e32 v180, v115
	v_exp_f32_e32 v232, v116
	v_exp_f32_e32 v233, v117
	v_exp_f32_e32 v234, v118
	v_exp_f32_e32 v235, v119
	v_add_f32_e32 v190, v190, v171
	v_add_f32_e32 v191, v191, v173
	v_add_f32_e32 v190, v190, v179
	v_add_f32_e32 v191, v191, v180
	v_add_f32_e32 v190, v190, v232
	v_add_f32_e32 v191, v191, v233
	v_add_f32_e32 v190, v190, v234
	v_add_f32_e32 v191, v191, v235
	v_cvt_pk_bf16_f32 v152, v171, v173
	v_cvt_pk_bf16_f32 v153, v179, v180
	v_cvt_pk_bf16_f32 v154, v232, v233
	v_cvt_pk_bf16_f32 v155, v234, v235
	v_exp_f32_e32 v171, v120
	v_exp_f32_e32 v173, v121
	v_exp_f32_e32 v179, v122
	v_exp_f32_e32 v180, v123
	v_exp_f32_e32 v232, v124
	v_exp_f32_e32 v233, v125
	v_exp_f32_e32 v234, v126
	v_exp_f32_e32 v235, v127
	v_add_f32_e32 v190, v190, v171
	v_add_f32_e32 v191, v191, v173
	v_add_f32_e32 v190, v190, v179
	v_add_f32_e32 v191, v191, v180
	v_add_f32_e32 v190, v190, v232
	v_add_f32_e32 v191, v191, v233
	v_add_f32_e32 v190, v190, v234
	v_add_f32_e32 v191, v191, v235
	v_add_f32_e32 v190, v190, v191
	v_cmp_ngt_f32_e32 vcc, 0x71800000, v190
	v_cvt_pk_bf16_f32 v156, v171, v173
	v_cvt_pk_bf16_f32 v157, v179, v180
	v_cvt_pk_bf16_f32 v158, v232, v233
	v_cvt_pk_bf16_f32 v159, v234, v235
	s_nop 0
	s_cbranch_vccnz .Lattn_redo_L0
	v_add_f32_e32 v167, v167, v190
	s_cmp_lg_u32 s14, 0
	s_cbranch_scc1 .Lattn_tb5
	s_waitcnt vmcnt(4)
	s_barrier
.Lattn_tb5:
	s_waitcnt lgkmcnt(5)
	v_mfma_f32_32x32x16_bf16 v[96:111], v[216:219], v[128:131], 0
	ds_read_b128 v[216:219], v185 offset:49152
	s_add_i32 s2, s42, 5
	s_waitcnt lgkmcnt(5)
	v_mfma_f32_32x32x16_bf16 v[112:127], v[220:223], v[128:131], 0
	ds_read_b128 v[220:223], v185 offset:53248
	s_and_b32 s2, s2, 31
	s_waitcnt lgkmcnt(5)
	v_mfma_f32_32x32x16_bf16 v[96:111], v[224:227], v[132:135], v[96:111]
	ds_read_b128 v[224:227], v187 offset:16384
	s_mul_i32 s2, s2, 0x44000
	s_waitcnt lgkmcnt(5)
	v_mfma_f32_32x32x16_bf16 v[112:127], v[228:231], v[132:135], v[112:127]
	ds_read_b128 v[228:231], v187 offset:20480
	s_add_u32 s48, s26, s2
	s_waitcnt lgkmcnt(5)
	v_mfma_f32_32x32x16_bf16 v[96:111], v[208:211], v[136:139], v[96:111]
	ds_read_b128 v[208:211], v187 offset:24576
	s_addc_u32 s49, s27, 0
	s_waitcnt lgkmcnt(5)
	v_mfma_f32_32x32x16_bf16 v[112:127], v[212:215], v[136:139], v[112:127]
	ds_read_b128 v[212:215], v187 offset:28672
	s_add_u32 s50, s48, 0x80
	s_waitcnt lgkmcnt(5)
	v_mfma_f32_32x32x16_bf16 v[96:111], v[216:219], v[140:143], v[96:111]
	ds_read_b128 v[216:219], v188 offset:16384
	s_addc_u32 s51, s49, 0
	s_waitcnt lgkmcnt(5)
	v_mfma_f32_32x32x16_bf16 v[112:127], v[220:223], v[140:143], v[112:127]
	ds_read_b128 v[220:223], v188 offset:20480
	s_add_i32 s2, s42, 3
	s_waitcnt lgkmcnt(5)
	v_mfma_f32_32x32x16_bf16 v[48:63], v[224:227], v[144:147], v[48:63]
	ds_read_b128 v[224:227], v188 offset:24576
	s_and_b32 s2, s2, 31
	s_waitcnt lgkmcnt(5)
	v_mfma_f32_32x32x16_bf16 v[32:47], v[228:231], v[144:147], v[32:47]
	ds_read_b128 v[228:231], v188 offset:28672
	s_lshl_b32 s2, s2, 7
	s_waitcnt lgkmcnt(5)
	v_mfma_f32_32x32x16_bf16 v[16:31], v[208:211], v[144:147], v[16:31]
	ds_read_b128 v[208:211], v186 offset:16384
	s_add_u32 s52, s10, s2
	s_waitcnt lgkmcnt(5)
	v_mfma_f32_32x32x16_bf16 v[0:15], v[212:215], v[144:147], v[0:15]
	ds_read_b128 v[212:215], v186 offset:20480
	s_addc_u32 s53, s11, 0
	s_waitcnt lgkmcnt(5)
	v_mfma_f32_32x32x16_bf16 v[48:63], v[216:219], v[148:151], v[48:63]
	ds_read_b128 v[216:219], v186 offset:24576
	s_add_u32 s54, s52, 0x204000
	s_waitcnt lgkmcnt(5)
	v_mfma_f32_32x32x16_bf16 v[32:47], v[220:223], v[148:151], v[32:47]
	ds_read_b128 v[220:223], v186 offset:28672
	s_addc_u32 s55, s53, 0
	s_waitcnt lgkmcnt(5)
	v_mfma_f32_32x32x16_bf16 v[16:31], v[224:227], v[148:151], v[16:31]
	ds_read_b128 v[224:227], v189 offset:16384
	s_waitcnt lgkmcnt(5)
	v_mfma_f32_32x32x16_bf16 v[0:15], v[228:231], v[148:151], v[0:15]
	ds_read_b128 v[228:231], v189 offset:20480
	s_waitcnt lgkmcnt(5)
	v_mfma_f32_32x32x16_bf16 v[48:63], v[208:211], v[152:155], v[48:63]
	ds_read_b128 v[208:211], v189 offset:24576
	s_waitcnt lgkmcnt(5)
	v_mfma_f32_32x32x16_bf16 v[32:47], v[212:215], v[152:155], v[32:47]
	ds_read_b128 v[212:215], v189 offset:28672
	s_waitcnt lgkmcnt(5)
	v_mfma_f32_32x32x16_bf16 v[16:31], v[216:219], v[152:155], v[16:31]
	s_waitcnt lgkmcnt(4)
	v_mfma_f32_32x32x16_bf16 v[0:15], v[220:223], v[152:155], v[0:15]
	s_waitcnt lgkmcnt(3)
	v_mfma_f32_32x32x16_bf16 v[48:63], v[224:227], v[156:159], v[48:63]
	s_waitcnt lgkmcnt(2)
	v_mfma_f32_32x32x16_bf16 v[32:47], v[228:231], v[156:159], v[32:47]
	s_waitcnt lgkmcnt(1)
	v_mfma_f32_32x32x16_bf16 v[16:31], v[208:211], v[156:159], v[16:31]
	s_waitcnt lgkmcnt(0)
	v_mfma_f32_32x32x16_bf16 v[0:15], v[212:215], v[156:159], v[0:15]
	s_cmp_lg_u32 s14, 0
	s_cbranch_scc0 .Lattn_tb6
	s_waitcnt vmcnt(4)
	s_barrier
.Lattn_tb6:
	ds_read_b128 v[216:219], v182 offset:0
	ds_read_b128 v[220:223], v182 offset:4096
	ds_read_b128 v[224:227], v183 offset:0
	ds_read_b128 v[228:231], v183 offset:4096
	ds_read_b128 v[208:211], v184 offset:0
	ds_read_b128 v[212:215], v184 offset:4096
	v_exp_f32_e32 v171, v64
	v_exp_f32_e32 v173, v65
	v_exp_f32_e32 v179, v66
	s_add_i32 m0, s5, 32768
	v_exp_f32_e32 v180, v67
	v_exp_f32_e32 v232, v68
	v_exp_f32_e32 v233, v69
	global_load_lds_dwordx4 v170, s[48:49]
	v_exp_f32_e32 v234, v70
	v_exp_f32_e32 v235, v71
	v_add_f32_e32 v190, v171, v173
	s_add_i32 m0, s5, 40960
	v_add_f32_e32 v191, v179, v180
	v_add_f32_e32 v190, v190, v232
	v_add_f32_e32 v191, v191, v233
	global_load_lds_dwordx4 v170, s[50:51]
	v_add_f32_e32 v190, v190, v234
	v_add_f32_e32 v191, v191, v235
	v_cvt_pk_bf16_f32 v144, v171, v173
	s_add_i32 m0, s5, 65536
	v_cvt_pk_bf16_f32 v145, v179, v180
	v_cvt_pk_bf16_f32 v146, v232, v233
	v_cvt_pk_bf16_f32 v147, v234, v235
	global_load_lds_dwordx4 v172, s[52:53]
	v_exp_f32_e32 v171, v72
	v_exp_f32_e32 v173, v73
	v_exp_f32_e32 v179, v74
	s_add_i32 m0, s5, 73728
	v_exp_f32_e32 v180, v75
	v_exp_f32_e32 v232, v76
	v_exp_f32_e32 v233, v77
	global_load_lds_dwordx4 v172, s[54:55]
	v_exp_f32_e32 v234, v78
	v_exp_f32_e32 v235, v79
	v_add_f32_e32 v190, v190, v171
	v_add_f32_e32 v191, v191, v173
	v_add_f32_e32 v190, v190, v179
	v_add_f32_e32 v191, v191, v180
	v_add_f32_e32 v190, v190, v232
	v_add_f32_e32 v191, v191, v233
	v_add_f32_e32 v190, v190, v234
	v_add_f32_e32 v191, v191, v235
	v_cvt_pk_bf16_f32 v148, v171, v173
	v_cvt_pk_bf16_f32 v149, v179, v180
	v_cvt_pk_bf16_f32 v150, v232, v233
	v_cvt_pk_bf16_f32 v151, v234, v235
	v_exp_f32_e32 v171, v80
	v_exp_f32_e32 v173, v81
	v_exp_f32_e32 v179, v82
	v_exp_f32_e32 v180, v83
	v_exp_f32_e32 v232, v84
	v_exp_f32_e32 v233, v85
	v_exp_f32_e32 v234, v86
	v_exp_f32_e32 v235, v87
	v_add_f32_e32 v190, v190, v171
	v_add_f32_e32 v191, v191, v173
	v_add_f32_e32 v190, v190, v179
	v_add_f32_e32 v191, v191, v180
	v_add_f32_e32 v190, v190, v232
	v_add_f32_e32 v191, v191, v233
	v_add_f32_e32 v190, v190, v234
	v_add_f32_e32 v191, v191, v235
	v_cvt_pk_bf16_f32 v152, v171, v173
	v_cvt_pk_bf16_f32 v153, v179, v180
	v_cvt_pk_bf16_f32 v154, v232, v233
	v_cvt_pk_bf16_f32 v155, v234, v235
	v_exp_f32_e32 v171, v88
	v_exp_f32_e32 v173, v89
	v_exp_f32_e32 v179, v90
	v_exp_f32_e32 v180, v91
	v_exp_f32_e32 v232, v92
	v_exp_f32_e32 v233, v93
	v_exp_f32_e32 v234, v94
	v_exp_f32_e32 v235, v95
	v_add_f32_e32 v190, v190, v171
	v_add_f32_e32 v191, v191, v173
	v_add_f32_e32 v190, v190, v179
	v_add_f32_e32 v191, v191, v180
	v_add_f32_e32 v190, v190, v232
	v_add_f32_e32 v191, v191, v233
	v_add_f32_e32 v190, v190, v234
	v_add_f32_e32 v191, v191, v235
	v_add_f32_e32 v190, v190, v191
	v_cmp_ngt_f32_e32 vcc, 0x71800000, v190
	v_cvt_pk_bf16_f32 v156, v171, v173
	v_cvt_pk_bf16_f32 v157, v179, v180
	v_cvt_pk_bf16_f32 v158, v232, v233
	v_cvt_pk_bf16_f32 v159, v234, v235
	s_nop 0
	s_cbranch_vccnz .Lattn_redo_L1
	v_add_f32_e32 v167, v167, v190
	s_cmp_lg_u32 s14, 0
	s_cbranch_scc1 .Lattn_tb7
	s_waitcnt vmcnt(4)
	s_barrier
.Lattn_tb7:
	s_waitcnt lgkmcnt(5)
	v_mfma_f32_32x32x16_bf16 v[64:79], v[216:219], v[128:131], 0
	ds_read_b128 v[216:219], v185 offset:0
	s_add_i32 s2, s42, 6
	s_waitcnt lgkmcnt(5)
	v_mfma_f32_32x32x16_bf16 v[80:95], v[220:223], v[128:131], 0
	ds_read_b128 v[220:223], v185 offset:4096
	s_and_b32 s2, s2, 31
	s_waitcnt lgkmcnt(5)
	v_mfma_f32_32x32x16_bf16 v[64:79], v[224:227], v[132:135], v[64:79]
	ds_read_b128 v[224:227], v187 offset:32768
	s_mul_i32 s2, s2, 0x44000
	s_waitcnt lgkmcnt(5)
	v_mfma_f32_32x32x16_bf16 v[80:95], v[228:231], v[132:135], v[80:95]
	ds_read_b128 v[228:231], v187 offset:36864
	s_add_u32 s48, s26, s2
	s_waitcnt lgkmcnt(5)
	v_mfma_f32_32x32x16_bf16 v[64:79], v[208:211], v[136:139], v[64:79]
	ds_read_b128 v[208:211], v187 offset:40960
	s_addc_u32 s49, s27, 0
	s_waitcnt lgkmcnt(5)
	v_mfma_f32_32x32x16_bf16 v[80:95], v[212:215], v[136:139], v[80:95]
	ds_read_b128 v[212:215], v187 offset:45056
	s_add_u32 s50, s48, 0x80
	s_waitcnt lgkmcnt(5)
	v_mfma_f32_32x32x16_bf16 v[64:79], v[216:219], v[140:143], v[64:79]
	ds_read_b128 v[216:219], v188 offset:32768
	s_addc_u32 s51, s49, 0
	s_waitcnt lgkmcnt(5)
	v_mfma_f32_32x32x16_bf16 v[80:95], v[220:223], v[140:143], v[80:95]
	ds_read_b128 v[220:223], v188 offset:36864
	s_add_i32 s2, s42, 4
	s_waitcnt lgkmcnt(5)
	v_mfma_f32_32x32x16_bf16 v[48:63], v[224:227], v[144:147], v[48:63]
	ds_read_b128 v[224:227], v188 offset:40960
	s_and_b32 s2, s2, 31
	s_waitcnt lgkmcnt(5)
	v_mfma_f32_32x32x16_bf16 v[32:47], v[228:231], v[144:147], v[32:47]
	ds_read_b128 v[228:231], v188 offset:45056
	s_lshl_b32 s2, s2, 7
	s_waitcnt lgkmcnt(5)
	v_mfma_f32_32x32x16_bf16 v[16:31], v[208:211], v[144:147], v[16:31]
	ds_read_b128 v[208:211], v186 offset:32768
	s_add_u32 s52, s10, s2
	s_waitcnt lgkmcnt(5)
	v_mfma_f32_32x32x16_bf16 v[0:15], v[212:215], v[144:147], v[0:15]
	ds_read_b128 v[212:215], v186 offset:36864
	s_addc_u32 s53, s11, 0
	s_waitcnt lgkmcnt(5)
	v_mfma_f32_32x32x16_bf16 v[48:63], v[216:219], v[148:151], v[48:63]
	ds_read_b128 v[216:219], v186 offset:40960
	s_add_u32 s54, s52, 0x204000
	s_waitcnt lgkmcnt(5)
	v_mfma_f32_32x32x16_bf16 v[32:47], v[220:223], v[148:151], v[32:47]
	ds_read_b128 v[220:223], v186 offset:45056
	s_addc_u32 s55, s53, 0
	s_waitcnt lgkmcnt(5)
	v_mfma_f32_32x32x16_bf16 v[16:31], v[224:227], v[148:151], v[16:31]
	ds_read_b128 v[224:227], v189 offset:32768
	s_waitcnt lgkmcnt(5)
	v_mfma_f32_32x32x16_bf16 v[0:15], v[228:231], v[148:151], v[0:15]
	ds_read_b128 v[228:231], v189 offset:36864
	s_waitcnt lgkmcnt(5)
	v_mfma_f32_32x32x16_bf16 v[48:63], v[208:211], v[152:155], v[48:63]
	ds_read_b128 v[208:211], v189 offset:40960
	s_waitcnt lgkmcnt(5)
	v_mfma_f32_32x32x16_bf16 v[32:47], v[212:215], v[152:155], v[32:47]
	ds_read_b128 v[212:215], v189 offset:45056
	s_waitcnt lgkmcnt(5)
	v_mfma_f32_32x32x16_bf16 v[16:31], v[216:219], v[152:155], v[16:31]
	s_waitcnt lgkmcnt(4)
	v_mfma_f32_32x32x16_bf16 v[0:15], v[220:223], v[152:155], v[0:15]
	s_waitcnt lgkmcnt(3)
	v_mfma_f32_32x32x16_bf16 v[48:63], v[224:227], v[156:159], v[48:63]
	s_waitcnt lgkmcnt(2)
	v_mfma_f32_32x32x16_bf16 v[32:47], v[228:231], v[156:159], v[32:47]
	s_waitcnt lgkmcnt(1)
	v_mfma_f32_32x32x16_bf16 v[16:31], v[208:211], v[156:159], v[16:31]
	s_waitcnt lgkmcnt(0)
	v_mfma_f32_32x32x16_bf16 v[0:15], v[212:215], v[156:159], v[0:15]
	s_cmp_lg_u32 s14, 0
	s_cbranch_scc0 .Lattn_tb8
	s_waitcnt vmcnt(4)
	s_barrier
.Lattn_tb8:
	ds_read_b128 v[216:219], v182 offset:16384
	ds_read_b128 v[220:223], v182 offset:20480
	ds_read_b128 v[224:227], v183 offset:16384
	ds_read_b128 v[228:231], v183 offset:20480
	ds_read_b128 v[208:211], v184 offset:16384
	ds_read_b128 v[212:215], v184 offset:20480
	v_exp_f32_e32 v171, v96
	v_exp_f32_e32 v173, v97
	v_exp_f32_e32 v179, v98
	s_add_i32 m0, s5, 49152
	v_exp_f32_e32 v180, v99
	v_exp_f32_e32 v232, v100
	v_exp_f32_e32 v233, v101
	global_load_lds_dwordx4 v170, s[48:49]
	v_exp_f32_e32 v234, v102
	v_exp_f32_e32 v235, v103
	v_add_f32_e32 v190, v171, v173
	s_add_i32 m0, s5, 57344
	v_add_f32_e32 v191, v179, v180
	v_add_f32_e32 v190, v190, v232
	v_add_f32_e32 v191, v191, v233
	global_load_lds_dwordx4 v170, s[50:51]
	v_add_f32_e32 v190, v190, v234
	v_add_f32_e32 v191, v191, v235
	v_cvt_pk_bf16_f32 v144, v171, v173
	s_add_i32 m0, s5, 81920
	v_cvt_pk_bf16_f32 v145, v179, v180
	v_cvt_pk_bf16_f32 v146, v232, v233
	v_cvt_pk_bf16_f32 v147, v234, v235
	global_load_lds_dwordx4 v172, s[52:53]
	v_exp_f32_e32 v171, v104
	v_exp_f32_e32 v173, v105
	v_exp_f32_e32 v179, v106
	s_add_i32 m0, s5, 90112
	v_exp_f32_e32 v180, v107
	v_exp_f32_e32 v232, v108
	v_exp_f32_e32 v233, v109
	global_load_lds_dwordx4 v172, s[54:55]
	v_exp_f32_e32 v234, v110
	v_exp_f32_e32 v235, v111
	v_add_f32_e32 v190, v190, v171
	v_add_f32_e32 v191, v191, v173
	v_add_f32_e32 v190, v190, v179
	v_add_f32_e32 v191, v191, v180
	v_add_f32_e32 v190, v190, v232
	v_add_f32_e32 v191, v191, v233
	v_add_f32_e32 v190, v190, v234
	v_add_f32_e32 v191, v191, v235
	v_cvt_pk_bf16_f32 v148, v171, v173
	v_cvt_pk_bf16_f32 v149, v179, v180
	v_cvt_pk_bf16_f32 v150, v232, v233
	v_cvt_pk_bf16_f32 v151, v234, v235
	v_exp_f32_e32 v171, v112
	v_exp_f32_e32 v173, v113
	v_exp_f32_e32 v179, v114
	v_exp_f32_e32 v180, v115
	v_exp_f32_e32 v232, v116
	v_exp_f32_e32 v233, v117
	v_exp_f32_e32 v234, v118
	v_exp_f32_e32 v235, v119
	v_add_f32_e32 v190, v190, v171
	v_add_f32_e32 v191, v191, v173
	v_add_f32_e32 v190, v190, v179
	v_add_f32_e32 v191, v191, v180
	v_add_f32_e32 v190, v190, v232
	v_add_f32_e32 v191, v191, v233
	v_add_f32_e32 v190, v190, v234
	v_add_f32_e32 v191, v191, v235
	v_cvt_pk_bf16_f32 v152, v171, v173
	v_cvt_pk_bf16_f32 v153, v179, v180
	v_cvt_pk_bf16_f32 v154, v232, v233
	v_cvt_pk_bf16_f32 v155, v234, v235
	v_exp_f32_e32 v171, v120
	v_exp_f32_e32 v173, v121
	v_exp_f32_e32 v179, v122
	v_exp_f32_e32 v180, v123
	v_exp_f32_e32 v232, v124
	v_exp_f32_e32 v233, v125
	v_exp_f32_e32 v234, v126
	v_exp_f32_e32 v235, v127
	v_add_f32_e32 v190, v190, v171
	v_add_f32_e32 v191, v191, v173
	v_add_f32_e32 v190, v190, v179
	v_add_f32_e32 v191, v191, v180
	v_add_f32_e32 v190, v190, v232
	v_add_f32_e32 v191, v191, v233
	v_add_f32_e32 v190, v190, v234
	v_add_f32_e32 v191, v191, v235
	v_add_f32_e32 v190, v190, v191
	v_cmp_ngt_f32_e32 vcc, 0x71800000, v190
	v_cvt_pk_bf16_f32 v156, v171, v173
	v_cvt_pk_bf16_f32 v157, v179, v180
	v_cvt_pk_bf16_f32 v158, v232, v233
	v_cvt_pk_bf16_f32 v159, v234, v235
	s_nop 0
	s_cbranch_vccnz .Lattn_redo_L2
	v_add_f32_e32 v167, v167, v190
	s_cmp_lg_u32 s14, 0
	s_cbranch_scc1 .Lattn_tb9
	s_waitcnt vmcnt(4)
	s_barrier
.Lattn_tb9:
	s_waitcnt lgkmcnt(5)
	v_mfma_f32_32x32x16_bf16 v[96:111], v[216:219], v[128:131], 0
	ds_read_b128 v[216:219], v185 offset:16384
	s_add_i32 s2, s42, 7
	s_waitcnt lgkmcnt(5)
	v_mfma_f32_32x32x16_bf16 v[112:127], v[220:223], v[128:131], 0
	ds_read_b128 v[220:223], v185 offset:20480
	s_and_b32 s2, s2, 31
	s_waitcnt lgkmcnt(5)
	v_mfma_f32_32x32x16_bf16 v[96:111], v[224:227], v[132:135], v[96:111]
	ds_read_b128 v[224:227], v187 offset:49152
	s_mul_i32 s2, s2, 0x44000
	s_waitcnt lgkmcnt(5)
	v_mfma_f32_32x32x16_bf16 v[112:127], v[228:231], v[132:135], v[112:127]
	ds_read_b128 v[228:231], v187 offset:53248
	s_add_u32 s48, s26, s2
	s_waitcnt lgkmcnt(5)
	v_mfma_f32_32x32x16_bf16 v[96:111], v[208:211], v[136:139], v[96:111]
	ds_read_b128 v[208:211], v187 offset:57344
	s_addc_u32 s49, s27, 0
	s_waitcnt lgkmcnt(5)
	v_mfma_f32_32x32x16_bf16 v[112:127], v[212:215], v[136:139], v[112:127]
	ds_read_b128 v[212:215], v187 offset:61440
	s_add_u32 s50, s48, 0x80
	s_waitcnt lgkmcnt(5)
	v_mfma_f32_32x32x16_bf16 v[96:111], v[216:219], v[140:143], v[96:111]
	ds_read_b128 v[216:219], v188 offset:49152
	s_addc_u32 s51, s49, 0
	s_waitcnt lgkmcnt(5)
	v_mfma_f32_32x32x16_bf16 v[112:127], v[220:223], v[140:143], v[112:127]
	ds_read_b128 v[220:223], v188 offset:53248
	s_add_i32 s2, s42, 5
	s_waitcnt lgkmcnt(5)
	v_mfma_f32_32x32x16_bf16 v[48:63], v[224:227], v[144:147], v[48:63]
	ds_read_b128 v[224:227], v188 offset:57344
	s_and_b32 s2, s2, 31
	s_waitcnt lgkmcnt(5)
	v_mfma_f32_32x32x16_bf16 v[32:47], v[228:231], v[144:147], v[32:47]
	ds_read_b128 v[228:231], v188 offset:61440
	s_lshl_b32 s2, s2, 7
	s_waitcnt lgkmcnt(5)
	v_mfma_f32_32x32x16_bf16 v[16:31], v[208:211], v[144:147], v[16:31]
	ds_read_b128 v[208:211], v186 offset:49152
	s_add_u32 s52, s10, s2
	s_waitcnt lgkmcnt(5)
	v_mfma_f32_32x32x16_bf16 v[0:15], v[212:215], v[144:147], v[0:15]
	ds_read_b128 v[212:215], v186 offset:53248
	s_addc_u32 s53, s11, 0
	s_waitcnt lgkmcnt(5)
	v_mfma_f32_32x32x16_bf16 v[48:63], v[216:219], v[148:151], v[48:63]
	ds_read_b128 v[216:219], v186 offset:57344
	s_add_u32 s54, s52, 0x204000
	s_waitcnt lgkmcnt(5)
	v_mfma_f32_32x32x16_bf16 v[32:47], v[220:223], v[148:151], v[32:47]
	ds_read_b128 v[220:223], v186 offset:61440
	s_addc_u32 s55, s53, 0
	s_waitcnt lgkmcnt(5)
	v_mfma_f32_32x32x16_bf16 v[16:31], v[224:227], v[148:151], v[16:31]
	ds_read_b128 v[224:227], v189 offset:49152
	s_waitcnt lgkmcnt(5)
	v_mfma_f32_32x32x16_bf16 v[0:15], v[228:231], v[148:151], v[0:15]
	ds_read_b128 v[228:231], v189 offset:53248
	s_waitcnt lgkmcnt(5)
	v_mfma_f32_32x32x16_bf16 v[48:63], v[208:211], v[152:155], v[48:63]
	ds_read_b128 v[208:211], v189 offset:57344
	s_waitcnt lgkmcnt(5)
	v_mfma_f32_32x32x16_bf16 v[32:47], v[212:215], v[152:155], v[32:47]
	ds_read_b128 v[212:215], v189 offset:61440
	s_waitcnt lgkmcnt(5)
	v_mfma_f32_32x32x16_bf16 v[16:31], v[216:219], v[152:155], v[16:31]
	s_waitcnt lgkmcnt(4)
	v_mfma_f32_32x32x16_bf16 v[0:15], v[220:223], v[152:155], v[0:15]
	s_waitcnt lgkmcnt(3)
	v_mfma_f32_32x32x16_bf16 v[48:63], v[224:227], v[156:159], v[48:63]
	s_waitcnt lgkmcnt(2)
	v_mfma_f32_32x32x16_bf16 v[32:47], v[228:231], v[156:159], v[32:47]
	s_waitcnt lgkmcnt(1)
	v_mfma_f32_32x32x16_bf16 v[16:31], v[208:211], v[156:159], v[16:31]
	s_waitcnt lgkmcnt(0)
	v_mfma_f32_32x32x16_bf16 v[0:15], v[212:215], v[156:159], v[0:15]
	s_cmp_lg_u32 s14, 0
	s_cbranch_scc0 .Lattn_tb10
	s_waitcnt vmcnt(4)
	s_barrier
.Lattn_tb10:
	ds_read_b128 v[216:219], v182 offset:32768
	ds_read_b128 v[220:223], v182 offset:36864
	ds_read_b128 v[224:227], v183 offset:32768
	ds_read_b128 v[228:231], v183 offset:36864
	ds_read_b128 v[208:211], v184 offset:32768
	ds_read_b128 v[212:215], v184 offset:36864
	v_exp_f32_e32 v171, v64
	v_exp_f32_e32 v173, v65
	v_exp_f32_e32 v179, v66
	s_add_i32 m0, s5, 0
	v_exp_f32_e32 v180, v67
	v_exp_f32_e32 v232, v68
	v_exp_f32_e32 v233, v69
	global_load_lds_dwordx4 v170, s[48:49]
	v_exp_f32_e32 v234, v70
	v_exp_f32_e32 v235, v71
	v_add_f32_e32 v190, v171, v173
	s_add_i32 m0, s5, 8192
	v_add_f32_e32 v191, v179, v180
	v_add_f32_e32 v190, v190, v232
	v_add_f32_e32 v191, v191, v233
	global_load_lds_dwordx4 v170, s[50:51]
	v_add_f32_e32 v190, v190, v234
	v_add_f32_e32 v191, v191, v235
	v_cvt_pk_bf16_f32 v144, v171, v173
	s_add_i32 m0, s5, 98304
	v_cvt_pk_bf16_f32 v145, v179, v180
	v_cvt_pk_bf16_f32 v146, v232, v233
	v_cvt_pk_bf16_f32 v147, v234, v235
	global_load_lds_dwordx4 v172, s[52:53]
	v_exp_f32_e32 v171, v72
	v_exp_f32_e32 v173, v73
	v_exp_f32_e32 v179, v74
	s_add_i32 m0, s5, 106496
	v_exp_f32_e32 v180, v75
	v_exp_f32_e32 v232, v76
	v_exp_f32_e32 v233, v77
	global_load_lds_dwordx4 v172, s[54:55]
	v_exp_f32_e32 v234, v78
	v_exp_f32_e32 v235, v79
	v_add_f32_e32 v190, v190, v171
	v_add_f32_e32 v191, v191, v173
	v_add_f32_e32 v190, v190, v179
	v_add_f32_e32 v191, v191, v180
	v_add_f32_e32 v190, v190, v232
	v_add_f32_e32 v191, v191, v233
	v_add_f32_e32 v190, v190, v234
	v_add_f32_e32 v191, v191, v235
	v_cvt_pk_bf16_f32 v148, v171, v173
	v_cvt_pk_bf16_f32 v149, v179, v180
	v_cvt_pk_bf16_f32 v150, v232, v233
	v_cvt_pk_bf16_f32 v151, v234, v235
	v_exp_f32_e32 v171, v80
	v_exp_f32_e32 v173, v81
	v_exp_f32_e32 v179, v82
	v_exp_f32_e32 v180, v83
	v_exp_f32_e32 v232, v84
	v_exp_f32_e32 v233, v85
	v_exp_f32_e32 v234, v86
	v_exp_f32_e32 v235, v87
	v_add_f32_e32 v190, v190, v171
	v_add_f32_e32 v191, v191, v173
	v_add_f32_e32 v190, v190, v179
	v_add_f32_e32 v191, v191, v180
	v_add_f32_e32 v190, v190, v232
	v_add_f32_e32 v191, v191, v233
	v_add_f32_e32 v190, v190, v234
	v_add_f32_e32 v191, v191, v235
	v_cvt_pk_bf16_f32 v152, v171, v173
	v_cvt_pk_bf16_f32 v153, v179, v180
	v_cvt_pk_bf16_f32 v154, v232, v233
	v_cvt_pk_bf16_f32 v155, v234, v235
	v_exp_f32_e32 v171, v88
	v_exp_f32_e32 v173, v89
	v_exp_f32_e32 v179, v90
	v_exp_f32_e32 v180, v91
	v_exp_f32_e32 v232, v92
	v_exp_f32_e32 v233, v93
	v_exp_f32_e32 v234, v94
	v_exp_f32_e32 v235, v95
	v_add_f32_e32 v190, v190, v171
	v_add_f32_e32 v191, v191, v173
	v_add_f32_e32 v190, v190, v179
	v_add_f32_e32 v191, v191, v180
	v_add_f32_e32 v190, v190, v232
	v_add_f32_e32 v191, v191, v233
	v_add_f32_e32 v190, v190, v234
	v_add_f32_e32 v191, v191, v235
	v_add_f32_e32 v190, v190, v191
	v_cmp_ngt_f32_e32 vcc, 0x71800000, v190
	v_cvt_pk_bf16_f32 v156, v171, v173
	v_cvt_pk_bf16_f32 v157, v179, v180
	v_cvt_pk_bf16_f32 v158, v232, v233
	v_cvt_pk_bf16_f32 v159, v234, v235
	s_nop 0
	s_cbranch_vccnz .Lattn_redo_L3
	v_add_f32_e32 v167, v167, v190
	s_add_i32 s42, s42, 4
	s_add_i32 s47, s47, -1
	s_cmp_lg_u32 s47, 0
	s_cbranch_scc1 .Lattn_loop_f
	s_cmp_lg_u32 s14, 0
	s_cbranch_scc1 .Lattn_tb11
	s_waitcnt vmcnt(4)
	s_barrier
.Lattn_tb11:
	s_waitcnt lgkmcnt(5)
	v_mfma_f32_32x32x16_bf16 v[64:79], v[216:219], v[128:131], 0
	ds_read_b128 v[216:219], v185 offset:32768
	s_add_i32 s2, s42, 2
	s_waitcnt lgkmcnt(5)
	v_mfma_f32_32x32x16_bf16 v[80:95], v[220:223], v[128:131], 0
	ds_read_b128 v[220:223], v185 offset:36864
	s_and_b32 s2, s2, 31
	s_waitcnt lgkmcnt(5)
	v_mfma_f32_32x32x16_bf16 v[64:79], v[224:227], v[132:135], v[64:79]
	ds_read_b128 v[224:227], v187 offset:0
	s_lshl_b32 s2, s2, 7
	s_waitcnt lgkmcnt(5)
	v_mfma_f32_32x32x16_bf16 v[80:95], v[228:231], v[132:135], v[80:95]
	ds_read_b128 v[228:231], v187 offset:4096
	s_add_u32 s52, s10, s2
	s_waitcnt lgkmcnt(5)
	v_mfma_f32_32x32x16_bf16 v[64:79], v[208:211], v[136:139], v[64:79]
	ds_read_b128 v[208:211], v187 offset:8192
	s_addc_u32 s53, s11, 0
	s_waitcnt lgkmcnt(5)
	v_mfma_f32_32x32x16_bf16 v[80:95], v[212:215], v[136:139], v[80:95]
	ds_read_b128 v[212:215], v187 offset:12288
	s_add_u32 s54, s52, 0x204000
	s_waitcnt lgkmcnt(5)
	v_mfma_f32_32x32x16_bf16 v[64:79], v[216:219], v[140:143], v[64:79]
	ds_read_b128 v[216:219], v188 offset:0
	s_addc_u32 s55, s53, 0
	s_waitcnt lgkmcnt(5)
	v_mfma_f32_32x32x16_bf16 v[80:95], v[220:223], v[140:143], v[80:95]
	ds_read_b128 v[220:223], v188 offset:4096
	s_waitcnt lgkmcnt(5)
	v_mfma_f32_32x32x16_bf16 v[48:63], v[224:227], v[144:147], v[48:63]
	ds_read_b128 v[224:227], v188 offset:8192
	s_waitcnt lgkmcnt(5)
	v_mfma_f32_32x32x16_bf16 v[32:47], v[228:231], v[144:147], v[32:47]
	ds_read_b128 v[228:231], v188 offset:12288
	s_waitcnt lgkmcnt(5)
	v_mfma_f32_32x32x16_bf16 v[16:31], v[208:211], v[144:147], v[16:31]
	ds_read_b128 v[208:211], v186 offset:0
	s_waitcnt lgkmcnt(5)
	v_mfma_f32_32x32x16_bf16 v[0:15], v[212:215], v[144:147], v[0:15]
	ds_read_b128 v[212:215], v186 offset:4096
	s_waitcnt lgkmcnt(5)
	v_mfma_f32_32x32x16_bf16 v[48:63], v[216:219], v[148:151], v[48:63]
	ds_read_b128 v[216:219], v186 offset:8192
	s_waitcnt lgkmcnt(5)
	v_mfma_f32_32x32x16_bf16 v[32:47], v[220:223], v[148:151], v[32:47]
	ds_read_b128 v[220:223], v186 offset:12288
	s_waitcnt lgkmcnt(5)
	v_mfma_f32_32x32x16_bf16 v[16:31], v[224:227], v[148:151], v[16:31]
	ds_read_b128 v[224:227], v189 offset:0
	s_waitcnt lgkmcnt(5)
	v_mfma_f32_32x32x16_bf16 v[0:15], v[228:231], v[148:151], v[0:15]
	ds_read_b128 v[228:231], v189 offset:4096
	s_waitcnt lgkmcnt(5)
	v_mfma_f32_32x32x16_bf16 v[48:63], v[208:211], v[152:155], v[48:63]
	ds_read_b128 v[208:211], v189 offset:8192
	s_waitcnt lgkmcnt(5)
	v_mfma_f32_32x32x16_bf16 v[32:47], v[212:215], v[152:155], v[32:47]
	ds_read_b128 v[212:215], v189 offset:12288
	s_waitcnt lgkmcnt(5)
	v_mfma_f32_32x32x16_bf16 v[16:31], v[216:219], v[152:155], v[16:31]
	s_waitcnt lgkmcnt(4)
	v_mfma_f32_32x32x16_bf16 v[0:15], v[220:223], v[152:155], v[0:15]
	s_waitcnt lgkmcnt(3)
	v_mfma_f32_32x32x16_bf16 v[48:63], v[224:227], v[156:159], v[48:63]
	s_waitcnt lgkmcnt(2)
	v_mfma_f32_32x32x16_bf16 v[32:47], v[228:231], v[156:159], v[32:47]
	s_waitcnt lgkmcnt(1)
	v_mfma_f32_32x32x16_bf16 v[16:31], v[208:211], v[156:159], v[16:31]
	s_waitcnt lgkmcnt(0)
	v_mfma_f32_32x32x16_bf16 v[0:15], v[212:215], v[156:159], v[0:15]
	s_cmp_lg_u32 s14, 0
	s_cbranch_scc0 .Lattn_tb12
	s_waitcnt vmcnt(4)
	s_barrier
.Lattn_tb12:
	ds_read_b128 v[216:219], v182 offset:49152
	ds_read_b128 v[220:223], v182 offset:53248
	ds_read_b128 v[224:227], v183 offset:49152
	ds_read_b128 v[228:231], v183 offset:53248
	ds_read_b128 v[208:211], v184 offset:49152
	ds_read_b128 v[212:215], v184 offset:53248
	v_exp_f32_e32 v171, v96
	v_exp_f32_e32 v173, v97
	v_exp_f32_e32 v179, v98
	s_add_i32 m0, s5, 114688
	v_exp_f32_e32 v180, v99
	v_exp_f32_e32 v232, v100
	v_exp_f32_e32 v233, v101
	global_load_lds_dwordx4 v172, s[52:53]
	v_exp_f32_e32 v234, v102
	v_exp_f32_e32 v235, v103
	v_add_f32_e32 v190, v171, v173
	s_add_i32 m0, s5, 122880
	v_add_f32_e32 v191, v179, v180
	v_add_f32_e32 v190, v190, v232
	v_add_f32_e32 v191, v191, v233
	global_load_lds_dwordx4 v172, s[54:55]
	v_add_f32_e32 v190, v190, v234
	v_add_f32_e32 v191, v191, v235
	v_cvt_pk_bf16_f32 v144, v171, v173
	v_cvt_pk_bf16_f32 v145, v179, v180
	v_cvt_pk_bf16_f32 v146, v232, v233
	v_cvt_pk_bf16_f32 v147, v234, v235
	v_exp_f32_e32 v171, v104
	v_exp_f32_e32 v173, v105
	v_exp_f32_e32 v179, v106
	v_exp_f32_e32 v180, v107
	v_exp_f32_e32 v232, v108
	v_exp_f32_e32 v233, v109
	v_exp_f32_e32 v234, v110
	v_exp_f32_e32 v235, v111
	v_add_f32_e32 v190, v190, v171
	v_add_f32_e32 v191, v191, v173
	v_add_f32_e32 v190, v190, v179
	v_add_f32_e32 v191, v191, v180
	v_add_f32_e32 v190, v190, v232
	v_add_f32_e32 v191, v191, v233
	v_add_f32_e32 v190, v190, v234
	v_add_f32_e32 v191, v191, v235
	v_cvt_pk_bf16_f32 v148, v171, v173
	v_cvt_pk_bf16_f32 v149, v179, v180
	v_cvt_pk_bf16_f32 v150, v232, v233
	v_cvt_pk_bf16_f32 v151, v234, v235
	v_exp_f32_e32 v171, v112
	v_exp_f32_e32 v173, v113
	v_exp_f32_e32 v179, v114
	v_exp_f32_e32 v180, v115
	v_exp_f32_e32 v232, v116
	v_exp_f32_e32 v233, v117
	v_exp_f32_e32 v234, v118
	v_exp_f32_e32 v235, v119
	v_add_f32_e32 v190, v190, v171
	v_add_f32_e32 v191, v191, v173
	v_add_f32_e32 v190, v190, v179
	v_add_f32_e32 v191, v191, v180
	v_add_f32_e32 v190, v190, v232
	v_add_f32_e32 v191, v191, v233
	v_add_f32_e32 v190, v190, v234
	v_add_f32_e32 v191, v191, v235
	v_cvt_pk_bf16_f32 v152, v171, v173
	v_cvt_pk_bf16_f32 v153, v179, v180
	v_cvt_pk_bf16_f32 v154, v232, v233
	v_cvt_pk_bf16_f32 v155, v234, v235
	v_exp_f32_e32 v171, v120
	v_exp_f32_e32 v173, v121
	v_exp_f32_e32 v179, v122
	v_exp_f32_e32 v180, v123
	v_exp_f32_e32 v232, v124
	v_exp_f32_e32 v233, v125
	v_exp_f32_e32 v234, v126
	v_exp_f32_e32 v235, v127
	v_add_f32_e32 v190, v190, v171
	v_add_f32_e32 v191, v191, v173
	v_add_f32_e32 v190, v190, v179
	v_add_f32_e32 v191, v191, v180
	v_add_f32_e32 v190, v190, v232
	v_add_f32_e32 v191, v191, v233
	v_add_f32_e32 v190, v190, v234
	v_add_f32_e32 v191, v191, v235
	v_add_f32_e32 v190, v190, v191
	v_cmp_ngt_f32_e32 vcc, 0x71800000, v190
	v_cvt_pk_bf16_f32 v156, v171, v173
	v_cvt_pk_bf16_f32 v157, v179, v180
	v_cvt_pk_bf16_f32 v158, v232, v233
	v_cvt_pk_bf16_f32 v159, v234, v235
	s_nop 0
	s_cbranch_vccnz .Lattn_redo_T29
	v_add_f32_e32 v167, v167, v190
	s_cmp_lg_u32 s14, 0
	s_cbranch_scc1 .Lattn_tb13
	s_waitcnt vmcnt(2)
	s_barrier
.Lattn_tb13:
	s_waitcnt lgkmcnt(5)
	v_mfma_f32_32x32x16_bf16 v[96:111], v[216:219], v[128:131], 0
	ds_read_b128 v[216:219], v185 offset:49152
	s_waitcnt lgkmcnt(5)
	v_mfma_f32_32x32x16_bf16 v[112:127], v[220:223], v[128:131], 0
	ds_read_b128 v[220:223], v185 offset:53248
	s_waitcnt lgkmcnt(5)
	v_mfma_f32_32x32x16_bf16 v[96:111], v[224:227], v[132:135], v[96:111]
	ds_read_b128 v[224:227], v187 offset:16384
	s_waitcnt lgkmcnt(5)
	v_mfma_f32_32x32x16_bf16 v[112:127], v[228:231], v[132:135], v[112:127]
	ds_read_b128 v[228:231], v187 offset:20480
	s_waitcnt lgkmcnt(5)
	v_mfma_f32_32x32x16_bf16 v[96:111], v[208:211], v[136:139], v[96:111]
	ds_read_b128 v[208:211], v187 offset:24576
	s_waitcnt lgkmcnt(5)
	v_mfma_f32_32x32x16_bf16 v[112:127], v[212:215], v[136:139], v[112:127]
	ds_read_b128 v[212:215], v187 offset:28672
	s_waitcnt lgkmcnt(5)
	v_mfma_f32_32x32x16_bf16 v[96:111], v[216:219], v[140:143], v[96:111]
	ds_read_b128 v[216:219], v188 offset:16384
	s_waitcnt lgkmcnt(5)
	v_mfma_f32_32x32x16_bf16 v[112:127], v[220:223], v[140:143], v[112:127]
	ds_read_b128 v[220:223], v188 offset:20480
	s_waitcnt lgkmcnt(5)
	v_mfma_f32_32x32x16_bf16 v[48:63], v[224:227], v[144:147], v[48:63]
	ds_read_b128 v[224:227], v188 offset:24576
	s_waitcnt lgkmcnt(5)
	v_mfma_f32_32x32x16_bf16 v[32:47], v[228:231], v[144:147], v[32:47]
	ds_read_b128 v[228:231], v188 offset:28672
	s_waitcnt lgkmcnt(5)
	v_mfma_f32_32x32x16_bf16 v[16:31], v[208:211], v[144:147], v[16:31]
	ds_read_b128 v[208:211], v186 offset:16384
	s_waitcnt lgkmcnt(5)
	v_mfma_f32_32x32x16_bf16 v[0:15], v[212:215], v[144:147], v[0:15]
	ds_read_b128 v[212:215], v186 offset:20480
	s_waitcnt lgkmcnt(5)
	v_mfma_f32_32x32x16_bf16 v[48:63], v[216:219], v[148:151], v[48:63]
	ds_read_b128 v[216:219], v186 offset:24576
	s_waitcnt lgkmcnt(5)
	v_mfma_f32_32x32x16_bf16 v[32:47], v[220:223], v[148:151], v[32:47]
	ds_read_b128 v[220:223], v186 offset:28672
	s_waitcnt lgkmcnt(5)
	v_mfma_f32_32x32x16_bf16 v[16:31], v[224:227], v[148:151], v[16:31]
	ds_read_b128 v[224:227], v189 offset:16384
	s_waitcnt lgkmcnt(5)
	v_mfma_f32_32x32x16_bf16 v[0:15], v[228:231], v[148:151], v[0:15]
	ds_read_b128 v[228:231], v189 offset:20480
	s_waitcnt lgkmcnt(5)
	v_mfma_f32_32x32x16_bf16 v[48:63], v[208:211], v[152:155], v[48:63]
	ds_read_b128 v[208:211], v189 offset:24576
	s_waitcnt lgkmcnt(5)
	v_mfma_f32_32x32x16_bf16 v[32:47], v[212:215], v[152:155], v[32:47]
	ds_read_b128 v[212:215], v189 offset:28672
	s_waitcnt lgkmcnt(5)
	v_mfma_f32_32x32x16_bf16 v[16:31], v[216:219], v[152:155], v[16:31]
	s_waitcnt lgkmcnt(4)
	v_mfma_f32_32x32x16_bf16 v[0:15], v[220:223], v[152:155], v[0:15]
	s_waitcnt lgkmcnt(3)
	v_mfma_f32_32x32x16_bf16 v[48:63], v[224:227], v[156:159], v[48:63]
	s_waitcnt lgkmcnt(2)
	v_mfma_f32_32x32x16_bf16 v[32:47], v[228:231], v[156:159], v[32:47]
	s_waitcnt lgkmcnt(1)
	v_mfma_f32_32x32x16_bf16 v[16:31], v[208:211], v[156:159], v[16:31]
	s_waitcnt lgkmcnt(0)
	v_mfma_f32_32x32x16_bf16 v[0:15], v[212:215], v[156:159], v[0:15]
	s_cmp_lg_u32 s14, 0
	s_cbranch_scc0 .Lattn_tb14
	s_waitcnt vmcnt(2)
	s_barrier

.Lattn_tb18:
	ds_read_b128 v[216:219], v182 offset:32768
	ds_read_b128 v[220:223], v182 offset:36864
	ds_read_b128 v[224:227], v183 offset:32768
	ds_read_b128 v[228:231], v183 offset:36864
	ds_read_b128 v[208:211], v184 offset:32768
	ds_read_b128 v[212:215], v184 offset:36864
	v_max3_f32 v254, v64, v65, v66
	s_add_i32 m0, s5, 0
	v_max3_f32 v255, v80, v81, v82
	global_load_lds_dwordx4 v170, s[48:49]
	v_max3_f32 v254, v254, v67, v68
	s_add_i32 m0, s5, 8192
	v_max3_f32 v255, v255, v83, v84
	global_load_lds_dwordx4 v170, s[50:51]
	v_max3_f32 v254, v254, v69, v70
	s_add_i32 m0, s5, 98304
	v_max3_f32 v255, v255, v85, v86
	global_load_lds_dwordx4 v172, s[52:53]
	v_max3_f32 v254, v254, v71, v72
	s_add_i32 m0, s5, 106496
	v_max3_f32 v255, v255, v87, v88
	global_load_lds_dwordx4 v172, s[54:55]
	v_max3_f32 v254, v254, v73, v74
	v_max3_f32 v255, v255, v89, v90
	v_max3_f32 v254, v254, v75, v76
	v_max3_f32 v255, v255, v91, v92
	v_max3_f32 v254, v254, v77, v78
	v_max3_f32 v255, v255, v93, v94
	v_max3_f32 v254, v254, v79, v95
	v_max_f32_e32 v254, v254, v255
	v_mov_b32_e32 v180, 0xc2800000
	v_cmp_lt_f32_e32 vcc, 0x4138aa3b, v254
	v_cmp_gt_f32_e64 s[40:41], v180, v254
	s_nop 4
	s_or_b64 vcc, vcc, s[40:41]
	s_nop 0

.Lattn_tb20:
	ds_read_b128 v[216:219], v182 offset:49152
	ds_read_b128 v[220:223], v182 offset:53248
	ds_read_b128 v[224:227], v183 offset:49152
	ds_read_b128 v[228:231], v183 offset:53248
	ds_read_b128 v[208:211], v184 offset:49152
	ds_read_b128 v[212:215], v184 offset:53248
	v_max3_f32 v254, v96, v97, v98
	s_add_i32 m0, s5, 16384
	v_max3_f32 v255, v112, v113, v114
	global_load_lds_dwordx4 v170, s[48:49]
	v_max3_f32 v254, v254, v99, v100
	s_add_i32 m0, s5, 24576
	v_max3_f32 v255, v255, v115, v116
	global_load_lds_dwordx4 v170, s[50:51]
	v_max3_f32 v254, v254, v101, v102
	s_add_i32 m0, s5, 114688
	v_max3_f32 v255, v255, v117, v118
	global_load_lds_dwordx4 v172, s[52:53]
	v_max3_f32 v254, v254, v103, v104
	s_add_i32 m0, s5, 122880
	v_max3_f32 v255, v255, v119, v120
	global_load_lds_dwordx4 v172, s[54:55]
	v_max3_f32 v254, v254, v105, v106
	v_max3_f32 v255, v255, v121, v122
	v_max3_f32 v254, v254, v107, v108
	v_max3_f32 v255, v255, v123, v124
	v_max3_f32 v254, v254, v109, v110
	v_max3_f32 v255, v255, v125, v126
	v_max3_f32 v254, v254, v111, v127
	v_max_f32_e32 v254, v254, v255
	v_mov_b32_e32 v255, v254
	s_nop 1
	v_permlane32_swap_b32_e32 v254, v255
	v_max_f32_e32 v254, v254, v255
	v_add_f32_e32 v180, 0x4138aa3b, v175
	v_cmp_gt_f32_e32 vcc, v254, v180
	s_nop 1
	v_cndmask_b32_e32 v180, v175, v254, vcc
	v_sub_f32_e32 v255, v175, v180
	v_exp_f32_e32 v174, v255
	v_mov_b32_e32 v175, v180
	v_sub_f32_e32 v96, v96, v175
	v_sub_f32_e32 v97, v97, v175
	v_sub_f32_e32 v98, v98, v175
	v_sub_f32_e32 v99, v99, v175
	v_sub_f32_e32 v100, v100, v175
	v_sub_f32_e32 v101, v101, v175
	v_sub_f32_e32 v102, v102, v175
	v_sub_f32_e32 v103, v103, v175
	v_exp_f32_e32 v96, v96
	v_exp_f32_e32 v97, v97
	v_exp_f32_e32 v98, v98
	v_exp_f32_e32 v99, v99
	v_exp_f32_e32 v100, v100
	v_exp_f32_e32 v101, v101
	v_exp_f32_e32 v102, v102
	v_exp_f32_e32 v103, v103
	v_add_f32_e32 v190, v96, v97
	v_add_f32_e32 v191, v98, v99
	v_add_f32_e32 v190, v190, v100
	v_add_f32_e32 v191, v191, v101
	v_add_f32_e32 v190, v190, v102
	v_add_f32_e32 v191, v191, v103
	v_cvt_pk_bf16_f32 v144, v96, v97
	v_cvt_pk_bf16_f32 v145, v98, v99
	v_cvt_pk_bf16_f32 v146, v100, v101
	v_cvt_pk_bf16_f32 v147, v102, v103
	v_sub_f32_e32 v104, v104, v175
	v_sub_f32_e32 v105, v105, v175
	v_sub_f32_e32 v106, v106, v175
	v_sub_f32_e32 v107, v107, v175
	v_sub_f32_e32 v108, v108, v175
	v_sub_f32_e32 v109, v109, v175
	v_sub_f32_e32 v110, v110, v175
	v_sub_f32_e32 v111, v111, v175
	v_exp_f32_e32 v104, v104
	v_exp_f32_e32 v105, v105
	v_exp_f32_e32 v106, v106
	v_exp_f32_e32 v107, v107
	v_exp_f32_e32 v108, v108
	v_exp_f32_e32 v109, v109
	v_exp_f32_e32 v110, v110
	v_exp_f32_e32 v111, v111
	v_add_f32_e32 v190, v190, v104
	v_add_f32_e32 v191, v191, v105
	v_add_f32_e32 v190, v190, v106
	v_add_f32_e32 v191, v191, v107
	v_add_f32_e32 v190, v190, v108
	v_add_f32_e32 v191, v191, v109
	v_add_f32_e32 v190, v190, v110
	v_add_f32_e32 v191, v191, v111
	v_cvt_pk_bf16_f32 v148, v104, v105
	v_cvt_pk_bf16_f32 v149, v106, v107
	v_cvt_pk_bf16_f32 v150, v108, v109
	v_cvt_pk_bf16_f32 v151, v110, v111
	v_sub_f32_e32 v112, v112, v175
	v_sub_f32_e32 v113, v113, v175
	v_sub_f32_e32 v114, v114, v175
	v_sub_f32_e32 v115, v115, v175
	v_sub_f32_e32 v116, v116, v175
	v_sub_f32_e32 v117, v117, v175
	v_sub_f32_e32 v118, v118, v175
	v_sub_f32_e32 v119, v119, v175
	v_exp_f32_e32 v112, v112
	v_exp_f32_e32 v113, v113
	v_exp_f32_e32 v114, v114
	v_exp_f32_e32 v115, v115
	v_exp_f32_e32 v116, v116
	v_exp_f32_e32 v117, v117
	v_exp_f32_e32 v118, v118
	v_exp_f32_e32 v119, v119
	v_add_f32_e32 v190, v190, v112
	v_add_f32_e32 v191, v191, v113
	v_add_f32_e32 v190, v190, v114
	v_add_f32_e32 v191, v191, v115
	v_add_f32_e32 v190, v190, v116
	v_add_f32_e32 v191, v191, v117
	v_add_f32_e32 v190, v190, v118
	v_add_f32_e32 v191, v191, v119
	v_cvt_pk_bf16_f32 v152, v112, v113
	v_cvt_pk_bf16_f32 v153, v114, v115
	v_cvt_pk_bf16_f32 v154, v116, v117
	v_cvt_pk_bf16_f32 v155, v118, v119
	v_sub_f32_e32 v120, v120, v175
	v_sub_f32_e32 v121, v121, v175
	v_sub_f32_e32 v122, v122, v175
	v_sub_f32_e32 v123, v123, v175
	v_sub_f32_e32 v124, v124, v175
	v_sub_f32_e32 v125, v125, v175
	v_sub_f32_e32 v126, v126, v175
	v_sub_f32_e32 v127, v127, v175
	v_exp_f32_e32 v120, v120
	v_exp_f32_e32 v121, v121
	v_exp_f32_e32 v122, v122
	v_exp_f32_e32 v123, v123
	v_exp_f32_e32 v124, v124
	v_exp_f32_e32 v125, v125
	v_exp_f32_e32 v126, v126
	v_exp_f32_e32 v127, v127
	v_add_f32_e32 v190, v190, v120
	v_add_f32_e32 v191, v191, v121
	v_add_f32_e32 v190, v190, v122
	v_add_f32_e32 v191, v191, v123
	v_add_f32_e32 v190, v190, v124
	v_add_f32_e32 v191, v191, v125
	v_add_f32_e32 v190, v190, v126
	v_add_f32_e32 v191, v191, v127
	v_cvt_pk_bf16_f32 v156, v120, v121
	v_cvt_pk_bf16_f32 v157, v122, v123
	v_cvt_pk_bf16_f32 v158, v124, v125
	v_cvt_pk_bf16_f32 v159, v126, v127
	v_add_f32_e32 v190, v190, v191
	v_fma_f32 v167, v167, v174, v190
	s_cbranch_vccz .Lattn_noresc_L0
	s_nop 7
	s_nop 7
	v_pk_mul_f32 v[0:1], v[0:1], v[174:175] op_sel_hi:[1,0]
	v_pk_mul_f32 v[2:3], v[2:3], v[174:175] op_sel_hi:[1,0]
	v_pk_mul_f32 v[4:5], v[4:5], v[174:175] op_sel_hi:[1,0]
	v_pk_mul_f32 v[6:7], v[6:7], v[174:175] op_sel_hi:[1,0]
	v_pk_mul_f32 v[8:9], v[8:9], v[174:175] op_sel_hi:[1,0]
	v_pk_mul_f32 v[10:11], v[10:11], v[174:175] op_sel_hi:[1,0]
	v_pk_mul_f32 v[12:13], v[12:13], v[174:175] op_sel_hi:[1,0]
	v_pk_mul_f32 v[14:15], v[14:15], v[174:175] op_sel_hi:[1,0]
	v_pk_mul_f32 v[16:17], v[16:17], v[174:175] op_sel_hi:[1,0]
	v_pk_mul_f32 v[18:19], v[18:19], v[174:175] op_sel_hi:[1,0]
	v_pk_mul_f32 v[20:21], v[20:21], v[174:175] op_sel_hi:[1,0]
	v_pk_mul_f32 v[22:23], v[22:23], v[174:175] op_sel_hi:[1,0]
	v_pk_mul_f32 v[24:25], v[24:25], v[174:175] op_sel_hi:[1,0]
	v_pk_mul_f32 v[26:27], v[26:27], v[174:175] op_sel_hi:[1,0]
	v_pk_mul_f32 v[28:29], v[28:29], v[174:175] op_sel_hi:[1,0]
	v_pk_mul_f32 v[30:31], v[30:31], v[174:175] op_sel_hi:[1,0]
	v_pk_mul_f32 v[32:33], v[32:33], v[174:175] op_sel_hi:[1,0]
	v_pk_mul_f32 v[34:35], v[34:35], v[174:175] op_sel_hi:[1,0]
	v_pk_mul_f32 v[36:37], v[36:37], v[174:175] op_sel_hi:[1,0]
	v_pk_mul_f32 v[38:39], v[38:39], v[174:175] op_sel_hi:[1,0]
	v_pk_mul_f32 v[40:41], v[40:41], v[174:175] op_sel_hi:[1,0]
	v_pk_mul_f32 v[42:43], v[42:43], v[174:175] op_sel_hi:[1,0]
	v_pk_mul_f32 v[44:45], v[44:45], v[174:175] op_sel_hi:[1,0]
	v_pk_mul_f32 v[46:47], v[46:47], v[174:175] op_sel_hi:[1,0]
	v_pk_mul_f32 v[48:49], v[48:49], v[174:175] op_sel_hi:[1,0]
	v_pk_mul_f32 v[50:51], v[50:51], v[174:175] op_sel_hi:[1,0]
	v_pk_mul_f32 v[52:53], v[52:53], v[174:175] op_sel_hi:[1,0]
	v_pk_mul_f32 v[54:55], v[54:55], v[174:175] op_sel_hi:[1,0]
	v_pk_mul_f32 v[56:57], v[56:57], v[174:175] op_sel_hi:[1,0]
	v_pk_mul_f32 v[58:59], v[58:59], v[174:175] op_sel_hi:[1,0]
	v_pk_mul_f32 v[60:61], v[60:61], v[174:175] op_sel_hi:[1,0]
	v_pk_mul_f32 v[62:63], v[62:63], v[174:175] op_sel_hi:[1,0]
	s_nop 1

.Lattn_tb22:
	ds_read_b128 v[216:219], v182 offset:0
	ds_read_b128 v[220:223], v182 offset:4096
	ds_read_b128 v[224:227], v183 offset:0
	ds_read_b128 v[228:231], v183 offset:4096
	ds_read_b128 v[208:211], v184 offset:0
	ds_read_b128 v[212:215], v184 offset:4096
	v_max3_f32 v254, v64, v65, v66
	s_add_i32 m0, s5, 32768
	v_max3_f32 v255, v80, v81, v82
	global_load_lds_dwordx4 v170, s[48:49]
	v_max3_f32 v254, v254, v67, v68
	s_add_i32 m0, s5, 40960
	v_max3_f32 v255, v255, v83, v84
	global_load_lds_dwordx4 v170, s[50:51]
	v_max3_f32 v254, v254, v69, v70
	s_add_i32 m0, s5, 65536
	v_max3_f32 v255, v255, v85, v86
	global_load_lds_dwordx4 v172, s[52:53]
	v_max3_f32 v254, v254, v71, v72
	s_add_i32 m0, s5, 73728
	v_max3_f32 v255, v255, v87, v88
	global_load_lds_dwordx4 v172, s[54:55]
	v_max3_f32 v254, v254, v73, v74
	v_max3_f32 v255, v255, v89, v90
	v_max3_f32 v254, v254, v75, v76
	v_max3_f32 v255, v255, v91, v92
	v_max3_f32 v254, v254, v77, v78
	v_max3_f32 v255, v255, v93, v94
	v_max3_f32 v254, v254, v79, v95
	v_max_f32_e32 v254, v254, v255
	v_mov_b32_e32 v255, v254
	s_nop 1
	v_permlane32_swap_b32_e32 v254, v255
	v_max_f32_e32 v254, v254, v255
	v_add_f32_e32 v180, 0x4138aa3b, v175
	v_cmp_gt_f32_e32 vcc, v254, v180
	s_nop 1
	v_cndmask_b32_e32 v180, v175, v254, vcc
	v_sub_f32_e32 v255, v175, v180
	v_exp_f32_e32 v174, v255
	v_mov_b32_e32 v175, v180
	v_sub_f32_e32 v64, v64, v175
	v_sub_f32_e32 v65, v65, v175
	v_sub_f32_e32 v66, v66, v175
	v_sub_f32_e32 v67, v67, v175
	v_sub_f32_e32 v68, v68, v175
	v_sub_f32_e32 v69, v69, v175
	v_sub_f32_e32 v70, v70, v175
	v_sub_f32_e32 v71, v71, v175
	v_exp_f32_e32 v64, v64
	v_exp_f32_e32 v65, v65
	v_exp_f32_e32 v66, v66
	v_exp_f32_e32 v67, v67
	v_exp_f32_e32 v68, v68
	v_exp_f32_e32 v69, v69
	v_exp_f32_e32 v70, v70
	v_exp_f32_e32 v71, v71
	v_add_f32_e32 v190, v64, v65
	v_add_f32_e32 v191, v66, v67
	v_add_f32_e32 v190, v190, v68
	v_add_f32_e32 v191, v191, v69
	v_add_f32_e32 v190, v190, v70
	v_add_f32_e32 v191, v191, v71
	v_cvt_pk_bf16_f32 v144, v64, v65
	v_cvt_pk_bf16_f32 v145, v66, v67
	v_cvt_pk_bf16_f32 v146, v68, v69
	v_cvt_pk_bf16_f32 v147, v70, v71
	v_sub_f32_e32 v72, v72, v175
	v_sub_f32_e32 v73, v73, v175
	v_sub_f32_e32 v74, v74, v175
	v_sub_f32_e32 v75, v75, v175
	v_sub_f32_e32 v76, v76, v175
	v_sub_f32_e32 v77, v77, v175
	v_sub_f32_e32 v78, v78, v175
	v_sub_f32_e32 v79, v79, v175
	v_exp_f32_e32 v72, v72
	v_exp_f32_e32 v73, v73
	v_exp_f32_e32 v74, v74
	v_exp_f32_e32 v75, v75
	v_exp_f32_e32 v76, v76
	v_exp_f32_e32 v77, v77
	v_exp_f32_e32 v78, v78
	v_exp_f32_e32 v79, v79
	v_add_f32_e32 v190, v190, v72
	v_add_f32_e32 v191, v191, v73
	v_add_f32_e32 v190, v190, v74
	v_add_f32_e32 v191, v191, v75
	v_add_f32_e32 v190, v190, v76
	v_add_f32_e32 v191, v191, v77
	v_add_f32_e32 v190, v190, v78
	v_add_f32_e32 v191, v191, v79
	v_cvt_pk_bf16_f32 v148, v72, v73
	v_cvt_pk_bf16_f32 v149, v74, v75
	v_cvt_pk_bf16_f32 v150, v76, v77
	v_cvt_pk_bf16_f32 v151, v78, v79
	v_sub_f32_e32 v80, v80, v175
	v_sub_f32_e32 v81, v81, v175
	v_sub_f32_e32 v82, v82, v175
	v_sub_f32_e32 v83, v83, v175
	v_sub_f32_e32 v84, v84, v175
	v_sub_f32_e32 v85, v85, v175
	v_sub_f32_e32 v86, v86, v175
	v_sub_f32_e32 v87, v87, v175
	v_exp_f32_e32 v80, v80
	v_exp_f32_e32 v81, v81
	v_exp_f32_e32 v82, v82
	v_exp_f32_e32 v83, v83
	v_exp_f32_e32 v84, v84
	v_exp_f32_e32 v85, v85
	v_exp_f32_e32 v86, v86
	v_exp_f32_e32 v87, v87
	v_add_f32_e32 v190, v190, v80
	v_add_f32_e32 v191, v191, v81
	v_add_f32_e32 v190, v190, v82
	v_add_f32_e32 v191, v191, v83
	v_add_f32_e32 v190, v190, v84
	v_add_f32_e32 v191, v191, v85
	v_add_f32_e32 v190, v190, v86
	v_add_f32_e32 v191, v191, v87
	v_cvt_pk_bf16_f32 v152, v80, v81
	v_cvt_pk_bf16_f32 v153, v82, v83
	v_cvt_pk_bf16_f32 v154, v84, v85
	v_cvt_pk_bf16_f32 v155, v86, v87
	v_sub_f32_e32 v88, v88, v175
	v_sub_f32_e32 v89, v89, v175
	v_sub_f32_e32 v90, v90, v175
	v_sub_f32_e32 v91, v91, v175
	v_sub_f32_e32 v92, v92, v175
	v_sub_f32_e32 v93, v93, v175
	v_sub_f32_e32 v94, v94, v175
	v_sub_f32_e32 v95, v95, v175
	v_exp_f32_e32 v88, v88
	v_exp_f32_e32 v89, v89
	v_exp_f32_e32 v90, v90
	v_exp_f32_e32 v91, v91
	v_exp_f32_e32 v92, v92
	v_exp_f32_e32 v93, v93
	v_exp_f32_e32 v94, v94
	v_exp_f32_e32 v95, v95
	v_add_f32_e32 v190, v190, v88
	v_add_f32_e32 v191, v191, v89
	v_add_f32_e32 v190, v190, v90
	v_add_f32_e32 v191, v191, v91
	v_add_f32_e32 v190, v190, v92
	v_add_f32_e32 v191, v191, v93
	v_add_f32_e32 v190, v190, v94
	v_add_f32_e32 v191, v191, v95
	v_cvt_pk_bf16_f32 v156, v88, v89
	v_cvt_pk_bf16_f32 v157, v90, v91
	v_cvt_pk_bf16_f32 v158, v92, v93
	v_cvt_pk_bf16_f32 v159, v94, v95
	v_add_f32_e32 v190, v190, v191
	v_fma_f32 v167, v167, v174, v190
	s_cbranch_vccz .Lattn_noresc_L1
	s_nop 7
	s_nop 7
	v_pk_mul_f32 v[0:1], v[0:1], v[174:175] op_sel_hi:[1,0]
	v_pk_mul_f32 v[2:3], v[2:3], v[174:175] op_sel_hi:[1,0]
	v_pk_mul_f32 v[4:5], v[4:5], v[174:175] op_sel_hi:[1,0]
	v_pk_mul_f32 v[6:7], v[6:7], v[174:175] op_sel_hi:[1,0]
	v_pk_mul_f32 v[8:9], v[8:9], v[174:175] op_sel_hi:[1,0]
	v_pk_mul_f32 v[10:11], v[10:11], v[174:175] op_sel_hi:[1,0]
	v_pk_mul_f32 v[12:13], v[12:13], v[174:175] op_sel_hi:[1,0]
	v_pk_mul_f32 v[14:15], v[14:15], v[174:175] op_sel_hi:[1,0]
	v_pk_mul_f32 v[16:17], v[16:17], v[174:175] op_sel_hi:[1,0]
	v_pk_mul_f32 v[18:19], v[18:19], v[174:175] op_sel_hi:[1,0]
	v_pk_mul_f32 v[20:21], v[20:21], v[174:175] op_sel_hi:[1,0]
	v_pk_mul_f32 v[22:23], v[22:23], v[174:175] op_sel_hi:[1,0]
	v_pk_mul_f32 v[24:25], v[24:25], v[174:175] op_sel_hi:[1,0]
	v_pk_mul_f32 v[26:27], v[26:27], v[174:175] op_sel_hi:[1,0]
	v_pk_mul_f32 v[28:29], v[28:29], v[174:175] op_sel_hi:[1,0]
	v_pk_mul_f32 v[30:31], v[30:31], v[174:175] op_sel_hi:[1,0]
	v_pk_mul_f32 v[32:33], v[32:33], v[174:175] op_sel_hi:[1,0]
	v_pk_mul_f32 v[34:35], v[34:35], v[174:175] op_sel_hi:[1,0]
	v_pk_mul_f32 v[36:37], v[36:37], v[174:175] op_sel_hi:[1,0]
	v_pk_mul_f32 v[38:39], v[38:39], v[174:175] op_sel_hi:[1,0]
	v_pk_mul_f32 v[40:41], v[40:41], v[174:175] op_sel_hi:[1,0]
	v_pk_mul_f32 v[42:43], v[42:43], v[174:175] op_sel_hi:[1,0]
	v_pk_mul_f32 v[44:45], v[44:45], v[174:175] op_sel_hi:[1,0]
	v_pk_mul_f32 v[46:47], v[46:47], v[174:175] op_sel_hi:[1,0]
	v_pk_mul_f32 v[48:49], v[48:49], v[174:175] op_sel_hi:[1,0]
	v_pk_mul_f32 v[50:51], v[50:51], v[174:175] op_sel_hi:[1,0]
	v_pk_mul_f32 v[52:53], v[52:53], v[174:175] op_sel_hi:[1,0]
	v_pk_mul_f32 v[54:55], v[54:55], v[174:175] op_sel_hi:[1,0]
	v_pk_mul_f32 v[56:57], v[56:57], v[174:175] op_sel_hi:[1,0]
	v_pk_mul_f32 v[58:59], v[58:59], v[174:175] op_sel_hi:[1,0]
	v_pk_mul_f32 v[60:61], v[60:61], v[174:175] op_sel_hi:[1,0]
	v_pk_mul_f32 v[62:63], v[62:63], v[174:175] op_sel_hi:[1,0]
	s_nop 1

.Lattn_tb24:
	ds_read_b128 v[216:219], v182 offset:16384
	ds_read_b128 v[220:223], v182 offset:20480
	ds_read_b128 v[224:227], v183 offset:16384
	ds_read_b128 v[228:231], v183 offset:20480
	ds_read_b128 v[208:211], v184 offset:16384
	ds_read_b128 v[212:215], v184 offset:20480
	v_max3_f32 v254, v96, v97, v98
	s_add_i32 m0, s5, 49152
	v_max3_f32 v255, v112, v113, v114
	global_load_lds_dwordx4 v170, s[48:49]
	v_max3_f32 v254, v254, v99, v100
	s_add_i32 m0, s5, 57344
	v_max3_f32 v255, v255, v115, v116
	global_load_lds_dwordx4 v170, s[50:51]
	v_max3_f32 v254, v254, v101, v102
	s_add_i32 m0, s5, 81920
	v_max3_f32 v255, v255, v117, v118
	global_load_lds_dwordx4 v172, s[52:53]
	v_max3_f32 v254, v254, v103, v104
	s_add_i32 m0, s5, 90112
	v_max3_f32 v255, v255, v119, v120
	global_load_lds_dwordx4 v172, s[54:55]
	v_max3_f32 v254, v254, v105, v106
	v_max3_f32 v255, v255, v121, v122
	v_max3_f32 v254, v254, v107, v108
	v_max3_f32 v255, v255, v123, v124
	v_max3_f32 v254, v254, v109, v110
	v_max3_f32 v255, v255, v125, v126
	v_max3_f32 v254, v254, v111, v127
	v_max_f32_e32 v254, v254, v255
	v_mov_b32_e32 v255, v254
	s_nop 1
	v_permlane32_swap_b32_e32 v254, v255
	v_max_f32_e32 v254, v254, v255
	v_add_f32_e32 v180, 0x4138aa3b, v175
	v_cmp_gt_f32_e32 vcc, v254, v180
	s_nop 1
	v_cndmask_b32_e32 v180, v175, v254, vcc
	v_sub_f32_e32 v255, v175, v180
	v_exp_f32_e32 v174, v255
	v_mov_b32_e32 v175, v180
	v_sub_f32_e32 v96, v96, v175
	v_sub_f32_e32 v97, v97, v175
	v_sub_f32_e32 v98, v98, v175
	v_sub_f32_e32 v99, v99, v175
	v_sub_f32_e32 v100, v100, v175
	v_sub_f32_e32 v101, v101, v175
	v_sub_f32_e32 v102, v102, v175
	v_sub_f32_e32 v103, v103, v175
	v_exp_f32_e32 v96, v96
	v_exp_f32_e32 v97, v97
	v_exp_f32_e32 v98, v98
	v_exp_f32_e32 v99, v99
	v_exp_f32_e32 v100, v100
	v_exp_f32_e32 v101, v101
	v_exp_f32_e32 v102, v102
	v_exp_f32_e32 v103, v103
	v_add_f32_e32 v190, v96, v97
	v_add_f32_e32 v191, v98, v99
	v_add_f32_e32 v190, v190, v100
	v_add_f32_e32 v191, v191, v101
	v_add_f32_e32 v190, v190, v102
	v_add_f32_e32 v191, v191, v103
	v_cvt_pk_bf16_f32 v144, v96, v97
	v_cvt_pk_bf16_f32 v145, v98, v99
	v_cvt_pk_bf16_f32 v146, v100, v101
	v_cvt_pk_bf16_f32 v147, v102, v103
	v_sub_f32_e32 v104, v104, v175
	v_sub_f32_e32 v105, v105, v175
	v_sub_f32_e32 v106, v106, v175
	v_sub_f32_e32 v107, v107, v175
	v_sub_f32_e32 v108, v108, v175
	v_sub_f32_e32 v109, v109, v175
	v_sub_f32_e32 v110, v110, v175
	v_sub_f32_e32 v111, v111, v175
	v_exp_f32_e32 v104, v104
	v_exp_f32_e32 v105, v105
	v_exp_f32_e32 v106, v106
	v_exp_f32_e32 v107, v107
	v_exp_f32_e32 v108, v108
	v_exp_f32_e32 v109, v109
	v_exp_f32_e32 v110, v110
	v_exp_f32_e32 v111, v111
	v_add_f32_e32 v190, v190, v104
	v_add_f32_e32 v191, v191, v105
	v_add_f32_e32 v190, v190, v106
	v_add_f32_e32 v191, v191, v107
	v_add_f32_e32 v190, v190, v108
	v_add_f32_e32 v191, v191, v109
	v_add_f32_e32 v190, v190, v110
	v_add_f32_e32 v191, v191, v111
	v_cvt_pk_bf16_f32 v148, v104, v105
	v_cvt_pk_bf16_f32 v149, v106, v107
	v_cvt_pk_bf16_f32 v150, v108, v109
	v_cvt_pk_bf16_f32 v151, v110, v111
	v_sub_f32_e32 v112, v112, v175
	v_sub_f32_e32 v113, v113, v175
	v_sub_f32_e32 v114, v114, v175
	v_sub_f32_e32 v115, v115, v175
	v_sub_f32_e32 v116, v116, v175
	v_sub_f32_e32 v117, v117, v175
	v_sub_f32_e32 v118, v118, v175
	v_sub_f32_e32 v119, v119, v175
	v_exp_f32_e32 v112, v112
	v_exp_f32_e32 v113, v113
	v_exp_f32_e32 v114, v114
	v_exp_f32_e32 v115, v115
	v_exp_f32_e32 v116, v116
	v_exp_f32_e32 v117, v117
	v_exp_f32_e32 v118, v118
	v_exp_f32_e32 v119, v119
	v_add_f32_e32 v190, v190, v112
	v_add_f32_e32 v191, v191, v113
	v_add_f32_e32 v190, v190, v114
	v_add_f32_e32 v191, v191, v115
	v_add_f32_e32 v190, v190, v116
	v_add_f32_e32 v191, v191, v117
	v_add_f32_e32 v190, v190, v118
	v_add_f32_e32 v191, v191, v119
	v_cvt_pk_bf16_f32 v152, v112, v113
	v_cvt_pk_bf16_f32 v153, v114, v115
	v_cvt_pk_bf16_f32 v154, v116, v117
	v_cvt_pk_bf16_f32 v155, v118, v119
	v_sub_f32_e32 v120, v120, v175
	v_sub_f32_e32 v121, v121, v175
	v_sub_f32_e32 v122, v122, v175
	v_sub_f32_e32 v123, v123, v175
	v_sub_f32_e32 v124, v124, v175
	v_sub_f32_e32 v125, v125, v175
	v_sub_f32_e32 v126, v126, v175
	v_sub_f32_e32 v127, v127, v175
	v_exp_f32_e32 v120, v120
	v_exp_f32_e32 v121, v121
	v_exp_f32_e32 v122, v122
	v_exp_f32_e32 v123, v123
	v_exp_f32_e32 v124, v124
	v_exp_f32_e32 v125, v125
	v_exp_f32_e32 v126, v126
	v_exp_f32_e32 v127, v127
	v_add_f32_e32 v190, v190, v120
	v_add_f32_e32 v191, v191, v121
	v_add_f32_e32 v190, v190, v122
	v_add_f32_e32 v191, v191, v123
	v_add_f32_e32 v190, v190, v124
	v_add_f32_e32 v191, v191, v125
	v_add_f32_e32 v190, v190, v126
	v_add_f32_e32 v191, v191, v127
	v_cvt_pk_bf16_f32 v156, v120, v121
	v_cvt_pk_bf16_f32 v157, v122, v123
	v_cvt_pk_bf16_f32 v158, v124, v125
	v_cvt_pk_bf16_f32 v159, v126, v127
	v_add_f32_e32 v190, v190, v191
	v_fma_f32 v167, v167, v174, v190
	s_cbranch_vccz .Lattn_noresc_L2
	s_nop 7
	s_nop 7
	v_pk_mul_f32 v[0:1], v[0:1], v[174:175] op_sel_hi:[1,0]
	v_pk_mul_f32 v[2:3], v[2:3], v[174:175] op_sel_hi:[1,0]
	v_pk_mul_f32 v[4:5], v[4:5], v[174:175] op_sel_hi:[1,0]
	v_pk_mul_f32 v[6:7], v[6:7], v[174:175] op_sel_hi:[1,0]
	v_pk_mul_f32 v[8:9], v[8:9], v[174:175] op_sel_hi:[1,0]
	v_pk_mul_f32 v[10:11], v[10:11], v[174:175] op_sel_hi:[1,0]
	v_pk_mul_f32 v[12:13], v[12:13], v[174:175] op_sel_hi:[1,0]
	v_pk_mul_f32 v[14:15], v[14:15], v[174:175] op_sel_hi:[1,0]
	v_pk_mul_f32 v[16:17], v[16:17], v[174:175] op_sel_hi:[1,0]
	v_pk_mul_f32 v[18:19], v[18:19], v[174:175] op_sel_hi:[1,0]
	v_pk_mul_f32 v[20:21], v[20:21], v[174:175] op_sel_hi:[1,0]
	v_pk_mul_f32 v[22:23], v[22:23], v[174:175] op_sel_hi:[1,0]
	v_pk_mul_f32 v[24:25], v[24:25], v[174:175] op_sel_hi:[1,0]
	v_pk_mul_f32 v[26:27], v[26:27], v[174:175] op_sel_hi:[1,0]
	v_pk_mul_f32 v[28:29], v[28:29], v[174:175] op_sel_hi:[1,0]
	v_pk_mul_f32 v[30:31], v[30:31], v[174:175] op_sel_hi:[1,0]
	v_pk_mul_f32 v[32:33], v[32:33], v[174:175] op_sel_hi:[1,0]
	v_pk_mul_f32 v[34:35], v[34:35], v[174:175] op_sel_hi:[1,0]
	v_pk_mul_f32 v[36:37], v[36:37], v[174:175] op_sel_hi:[1,0]
	v_pk_mul_f32 v[38:39], v[38:39], v[174:175] op_sel_hi:[1,0]
	v_pk_mul_f32 v[40:41], v[40:41], v[174:175] op_sel_hi:[1,0]
	v_pk_mul_f32 v[42:43], v[42:43], v[174:175] op_sel_hi:[1,0]
	v_pk_mul_f32 v[44:45], v[44:45], v[174:175] op_sel_hi:[1,0]
	v_pk_mul_f32 v[46:47], v[46:47], v[174:175] op_sel_hi:[1,0]
	v_pk_mul_f32 v[48:49], v[48:49], v[174:175] op_sel_hi:[1,0]
	v_pk_mul_f32 v[50:51], v[50:51], v[174:175] op_sel_hi:[1,0]
	v_pk_mul_f32 v[52:53], v[52:53], v[174:175] op_sel_hi:[1,0]
	v_pk_mul_f32 v[54:55], v[54:55], v[174:175] op_sel_hi:[1,0]
	v_pk_mul_f32 v[56:57], v[56:57], v[174:175] op_sel_hi:[1,0]
	v_pk_mul_f32 v[58:59], v[58:59], v[174:175] op_sel_hi:[1,0]
	v_pk_mul_f32 v[60:61], v[60:61], v[174:175] op_sel_hi:[1,0]
	v_pk_mul_f32 v[62:63], v[62:63], v[174:175] op_sel_hi:[1,0]
	s_nop 1

.Lattn_tb26:
	ds_read_b128 v[216:219], v182 offset:32768
	ds_read_b128 v[220:223], v182 offset:36864
	ds_read_b128 v[224:227], v183 offset:32768
	ds_read_b128 v[228:231], v183 offset:36864
	ds_read_b128 v[208:211], v184 offset:32768
	ds_read_b128 v[212:215], v184 offset:36864
	v_max3_f32 v254, v64, v65, v66
	s_add_i32 m0, s5, 0
	v_max3_f32 v255, v80, v81, v82
	global_load_lds_dwordx4 v170, s[48:49]
	v_max3_f32 v254, v254, v67, v68
	s_add_i32 m0, s5, 8192
	v_max3_f32 v255, v255, v83, v84
	global_load_lds_dwordx4 v170, s[50:51]
	v_max3_f32 v254, v254, v69, v70
	s_add_i32 m0, s5, 98304
	v_max3_f32 v255, v255, v85, v86
	global_load_lds_dwordx4 v172, s[52:53]
	v_max3_f32 v254, v254, v71, v72
	s_add_i32 m0, s5, 106496
	v_max3_f32 v255, v255, v87, v88
	global_load_lds_dwordx4 v172, s[54:55]
	v_max3_f32 v254, v254, v73, v74
	v_max3_f32 v255, v255, v89, v90
	v_max3_f32 v254, v254, v75, v76
	v_max3_f32 v255, v255, v91, v92
	v_max3_f32 v254, v254, v77, v78
	v_max3_f32 v255, v255, v93, v94
	v_max3_f32 v254, v254, v79, v95
	v_max_f32_e32 v254, v254, v255
	v_mov_b32_e32 v255, v254
	s_nop 1
	v_permlane32_swap_b32_e32 v254, v255
	v_max_f32_e32 v254, v254, v255
	v_add_f32_e32 v180, 0x4138aa3b, v175
	v_cmp_gt_f32_e32 vcc, v254, v180
	s_nop 1
	v_cndmask_b32_e32 v180, v175, v254, vcc
	v_sub_f32_e32 v255, v175, v180
	v_exp_f32_e32 v174, v255
	v_mov_b32_e32 v175, v180
	v_sub_f32_e32 v64, v64, v175
	v_sub_f32_e32 v65, v65, v175
	v_sub_f32_e32 v66, v66, v175
	v_sub_f32_e32 v67, v67, v175
	v_sub_f32_e32 v68, v68, v175
	v_sub_f32_e32 v69, v69, v175
	v_sub_f32_e32 v70, v70, v175
	v_sub_f32_e32 v71, v71, v175
	v_exp_f32_e32 v64, v64
	v_exp_f32_e32 v65, v65
	v_exp_f32_e32 v66, v66
	v_exp_f32_e32 v67, v67
	v_exp_f32_e32 v68, v68
	v_exp_f32_e32 v69, v69
	v_exp_f32_e32 v70, v70
	v_exp_f32_e32 v71, v71
	v_add_f32_e32 v190, v64, v65
	v_add_f32_e32 v191, v66, v67
	v_add_f32_e32 v190, v190, v68
	v_add_f32_e32 v191, v191, v69
	v_add_f32_e32 v190, v190, v70
	v_add_f32_e32 v191, v191, v71
	v_cvt_pk_bf16_f32 v144, v64, v65
	v_cvt_pk_bf16_f32 v145, v66, v67
	v_cvt_pk_bf16_f32 v146, v68, v69
	v_cvt_pk_bf16_f32 v147, v70, v71
	v_sub_f32_e32 v72, v72, v175
	v_sub_f32_e32 v73, v73, v175
	v_sub_f32_e32 v74, v74, v175
	v_sub_f32_e32 v75, v75, v175
	v_sub_f32_e32 v76, v76, v175
	v_sub_f32_e32 v77, v77, v175
	v_sub_f32_e32 v78, v78, v175
	v_sub_f32_e32 v79, v79, v175
	v_exp_f32_e32 v72, v72
	v_exp_f32_e32 v73, v73
	v_exp_f32_e32 v74, v74
	v_exp_f32_e32 v75, v75
	v_exp_f32_e32 v76, v76
	v_exp_f32_e32 v77, v77
	v_exp_f32_e32 v78, v78
	v_exp_f32_e32 v79, v79
	v_add_f32_e32 v190, v190, v72
	v_add_f32_e32 v191, v191, v73
	v_add_f32_e32 v190, v190, v74
	v_add_f32_e32 v191, v191, v75
	v_add_f32_e32 v190, v190, v76
	v_add_f32_e32 v191, v191, v77
	v_add_f32_e32 v190, v190, v78
	v_add_f32_e32 v191, v191, v79
	v_cvt_pk_bf16_f32 v148, v72, v73
	v_cvt_pk_bf16_f32 v149, v74, v75
	v_cvt_pk_bf16_f32 v150, v76, v77
	v_cvt_pk_bf16_f32 v151, v78, v79
	v_sub_f32_e32 v80, v80, v175
	v_sub_f32_e32 v81, v81, v175
	v_sub_f32_e32 v82, v82, v175
	v_sub_f32_e32 v83, v83, v175
	v_sub_f32_e32 v84, v84, v175
	v_sub_f32_e32 v85, v85, v175
	v_sub_f32_e32 v86, v86, v175
	v_sub_f32_e32 v87, v87, v175
	v_exp_f32_e32 v80, v80
	v_exp_f32_e32 v81, v81
	v_exp_f32_e32 v82, v82
	v_exp_f32_e32 v83, v83
	v_exp_f32_e32 v84, v84
	v_exp_f32_e32 v85, v85
	v_exp_f32_e32 v86, v86
	v_exp_f32_e32 v87, v87
	v_add_f32_e32 v190, v190, v80
	v_add_f32_e32 v191, v191, v81
	v_add_f32_e32 v190, v190, v82
	v_add_f32_e32 v191, v191, v83
	v_add_f32_e32 v190, v190, v84
	v_add_f32_e32 v191, v191, v85
	v_add_f32_e32 v190, v190, v86
	v_add_f32_e32 v191, v191, v87
	v_cvt_pk_bf16_f32 v152, v80, v81
	v_cvt_pk_bf16_f32 v153, v82, v83
	v_cvt_pk_bf16_f32 v154, v84, v85
	v_cvt_pk_bf16_f32 v155, v86, v87
	v_sub_f32_e32 v88, v88, v175
	v_sub_f32_e32 v89, v89, v175
	v_sub_f32_e32 v90, v90, v175
	v_sub_f32_e32 v91, v91, v175
	v_sub_f32_e32 v92, v92, v175
	v_sub_f32_e32 v93, v93, v175
	v_sub_f32_e32 v94, v94, v175
	v_sub_f32_e32 v95, v95, v175
	v_exp_f32_e32 v88, v88
	v_exp_f32_e32 v89, v89
	v_exp_f32_e32 v90, v90
	v_exp_f32_e32 v91, v91
	v_exp_f32_e32 v92, v92
	v_exp_f32_e32 v93, v93
	v_exp_f32_e32 v94, v94
	v_exp_f32_e32 v95, v95
	v_add_f32_e32 v190, v190, v88
	v_add_f32_e32 v191, v191, v89
	v_add_f32_e32 v190, v190, v90
	v_add_f32_e32 v191, v191, v91
	v_add_f32_e32 v190, v190, v92
	v_add_f32_e32 v191, v191, v93
	v_add_f32_e32 v190, v190, v94
	v_add_f32_e32 v191, v191, v95
	v_cvt_pk_bf16_f32 v156, v88, v89
	v_cvt_pk_bf16_f32 v157, v90, v91
	v_cvt_pk_bf16_f32 v158, v92, v93
	v_cvt_pk_bf16_f32 v159, v94, v95
	v_add_f32_e32 v190, v190, v191
	v_fma_f32 v167, v167, v174, v190
	s_cbranch_vccz .Lattn_noresc_L3
	s_nop 7
	s_nop 7
	v_pk_mul_f32 v[0:1], v[0:1], v[174:175] op_sel_hi:[1,0]
	v_pk_mul_f32 v[2:3], v[2:3], v[174:175] op_sel_hi:[1,0]
	v_pk_mul_f32 v[4:5], v[4:5], v[174:175] op_sel_hi:[1,0]
	v_pk_mul_f32 v[6:7], v[6:7], v[174:175] op_sel_hi:[1,0]
	v_pk_mul_f32 v[8:9], v[8:9], v[174:175] op_sel_hi:[1,0]
	v_pk_mul_f32 v[10:11], v[10:11], v[174:175] op_sel_hi:[1,0]
	v_pk_mul_f32 v[12:13], v[12:13], v[174:175] op_sel_hi:[1,0]
	v_pk_mul_f32 v[14:15], v[14:15], v[174:175] op_sel_hi:[1,0]
	v_pk_mul_f32 v[16:17], v[16:17], v[174:175] op_sel_hi:[1,0]
	v_pk_mul_f32 v[18:19], v[18:19], v[174:175] op_sel_hi:[1,0]
	v_pk_mul_f32 v[20:21], v[20:21], v[174:175] op_sel_hi:[1,0]
	v_pk_mul_f32 v[22:23], v[22:23], v[174:175] op_sel_hi:[1,0]
	v_pk_mul_f32 v[24:25], v[24:25], v[174:175] op_sel_hi:[1,0]
	v_pk_mul_f32 v[26:27], v[26:27], v[174:175] op_sel_hi:[1,0]
	v_pk_mul_f32 v[28:29], v[28:29], v[174:175] op_sel_hi:[1,0]
	v_pk_mul_f32 v[30:31], v[30:31], v[174:175] op_sel_hi:[1,0]
	v_pk_mul_f32 v[32:33], v[32:33], v[174:175] op_sel_hi:[1,0]
	v_pk_mul_f32 v[34:35], v[34:35], v[174:175] op_sel_hi:[1,0]
	v_pk_mul_f32 v[36:37], v[36:37], v[174:175] op_sel_hi:[1,0]
	v_pk_mul_f32 v[38:39], v[38:39], v[174:175] op_sel_hi:[1,0]
	v_pk_mul_f32 v[40:41], v[40:41], v[174:175] op_sel_hi:[1,0]
	v_pk_mul_f32 v[42:43], v[42:43], v[174:175] op_sel_hi:[1,0]
	v_pk_mul_f32 v[44:45], v[44:45], v[174:175] op_sel_hi:[1,0]
	v_pk_mul_f32 v[46:47], v[46:47], v[174:175] op_sel_hi:[1,0]
	v_pk_mul_f32 v[48:49], v[48:49], v[174:175] op_sel_hi:[1,0]
	v_pk_mul_f32 v[50:51], v[50:51], v[174:175] op_sel_hi:[1,0]
	v_pk_mul_f32 v[52:53], v[52:53], v[174:175] op_sel_hi:[1,0]
	v_pk_mul_f32 v[54:55], v[54:55], v[174:175] op_sel_hi:[1,0]
	v_pk_mul_f32 v[56:57], v[56:57], v[174:175] op_sel_hi:[1,0]
	v_pk_mul_f32 v[58:59], v[58:59], v[174:175] op_sel_hi:[1,0]
	v_pk_mul_f32 v[60:61], v[60:61], v[174:175] op_sel_hi:[1,0]
	v_pk_mul_f32 v[62:63], v[62:63], v[174:175] op_sel_hi:[1,0]
	s_nop 1

.Lattn_tb28:
	ds_read_b128 v[216:219], v182 offset:49152
	ds_read_b128 v[220:223], v182 offset:53248
	ds_read_b128 v[224:227], v183 offset:49152
	ds_read_b128 v[228:231], v183 offset:53248
	ds_read_b128 v[208:211], v184 offset:49152
	ds_read_b128 v[212:215], v184 offset:53248
	v_max3_f32 v254, v96, v97, v98
	s_add_i32 m0, s5, 114688
	v_max3_f32 v255, v112, v113, v114
	global_load_lds_dwordx4 v172, s[52:53]
	v_max3_f32 v254, v254, v99, v100
	s_add_i32 m0, s5, 122880
	v_max3_f32 v255, v255, v115, v116
	global_load_lds_dwordx4 v172, s[54:55]
	v_max3_f32 v254, v254, v101, v102
	v_max3_f32 v255, v255, v117, v118
	v_max3_f32 v254, v254, v103, v104
	v_max3_f32 v255, v255, v119, v120
	v_max3_f32 v254, v254, v105, v106
	v_max3_f32 v255, v255, v121, v122
	v_max3_f32 v254, v254, v107, v108
	v_max3_f32 v255, v255, v123, v124
	v_max3_f32 v254, v254, v109, v110
	v_max3_f32 v255, v255, v125, v126
	v_max3_f32 v254, v254, v111, v127
	v_max_f32_e32 v254, v254, v255
	v_mov_b32_e32 v255, v254
	s_nop 1
	v_permlane32_swap_b32_e32 v254, v255
	v_max_f32_e32 v254, v254, v255
	v_add_f32_e32 v180, 0x4138aa3b, v175
	v_cmp_gt_f32_e32 vcc, v254, v180
	s_nop 1
	v_cndmask_b32_e32 v180, v175, v254, vcc
	v_sub_f32_e32 v255, v175, v180
	v_exp_f32_e32 v174, v255
	v_mov_b32_e32 v175, v180
	v_sub_f32_e32 v96, v96, v175
	v_sub_f32_e32 v97, v97, v175
	v_sub_f32_e32 v98, v98, v175
	v_sub_f32_e32 v99, v99, v175
	v_sub_f32_e32 v100, v100, v175
	v_sub_f32_e32 v101, v101, v175
	v_sub_f32_e32 v102, v102, v175
	v_sub_f32_e32 v103, v103, v175
	v_exp_f32_e32 v96, v96
	v_exp_f32_e32 v97, v97
	v_exp_f32_e32 v98, v98
	v_exp_f32_e32 v99, v99
	v_exp_f32_e32 v100, v100
	v_exp_f32_e32 v101, v101
	v_exp_f32_e32 v102, v102
	v_exp_f32_e32 v103, v103
	v_add_f32_e32 v190, v96, v97
	v_add_f32_e32 v191, v98, v99
	v_add_f32_e32 v190, v190, v100
	v_add_f32_e32 v191, v191, v101
	v_add_f32_e32 v190, v190, v102
	v_add_f32_e32 v191, v191, v103
	v_cvt_pk_bf16_f32 v144, v96, v97
	v_cvt_pk_bf16_f32 v145, v98, v99
	v_cvt_pk_bf16_f32 v146, v100, v101
	v_cvt_pk_bf16_f32 v147, v102, v103
	v_sub_f32_e32 v104, v104, v175
	v_sub_f32_e32 v105, v105, v175
	v_sub_f32_e32 v106, v106, v175
	v_sub_f32_e32 v107, v107, v175
	v_sub_f32_e32 v108, v108, v175
	v_sub_f32_e32 v109, v109, v175
	v_sub_f32_e32 v110, v110, v175
	v_sub_f32_e32 v111, v111, v175
	v_exp_f32_e32 v104, v104
	v_exp_f32_e32 v105, v105
	v_exp_f32_e32 v106, v106
	v_exp_f32_e32 v107, v107
	v_exp_f32_e32 v108, v108
	v_exp_f32_e32 v109, v109
	v_exp_f32_e32 v110, v110
	v_exp_f32_e32 v111, v111
	v_add_f32_e32 v190, v190, v104
	v_add_f32_e32 v191, v191, v105
	v_add_f32_e32 v190, v190, v106
	v_add_f32_e32 v191, v191, v107
	v_add_f32_e32 v190, v190, v108
	v_add_f32_e32 v191, v191, v109
	v_add_f32_e32 v190, v190, v110
	v_add_f32_e32 v191, v191, v111
	v_cvt_pk_bf16_f32 v148, v104, v105
	v_cvt_pk_bf16_f32 v149, v106, v107
	v_cvt_pk_bf16_f32 v150, v108, v109
	v_cvt_pk_bf16_f32 v151, v110, v111
	v_sub_f32_e32 v112, v112, v175
	v_sub_f32_e32 v113, v113, v175
	v_sub_f32_e32 v114, v114, v175
	v_sub_f32_e32 v115, v115, v175
	v_sub_f32_e32 v116, v116, v175
	v_sub_f32_e32 v117, v117, v175
	v_sub_f32_e32 v118, v118, v175
	v_sub_f32_e32 v119, v119, v175
	v_exp_f32_e32 v112, v112
	v_exp_f32_e32 v113, v113
	v_exp_f32_e32 v114, v114
	v_exp_f32_e32 v115, v115
	v_exp_f32_e32 v116, v116
	v_exp_f32_e32 v117, v117
	v_exp_f32_e32 v118, v118
	v_exp_f32_e32 v119, v119
	v_add_f32_e32 v190, v190, v112
	v_add_f32_e32 v191, v191, v113
	v_add_f32_e32 v190, v190, v114
	v_add_f32_e32 v191, v191, v115
	v_add_f32_e32 v190, v190, v116
	v_add_f32_e32 v191, v191, v117
	v_add_f32_e32 v190, v190, v118
	v_add_f32_e32 v191, v191, v119
	v_cvt_pk_bf16_f32 v152, v112, v113
	v_cvt_pk_bf16_f32 v153, v114, v115
	v_cvt_pk_bf16_f32 v154, v116, v117
	v_cvt_pk_bf16_f32 v155, v118, v119
	v_sub_f32_e32 v120, v120, v175
	v_sub_f32_e32 v121, v121, v175
	v_sub_f32_e32 v122, v122, v175
	v_sub_f32_e32 v123, v123, v175
	v_sub_f32_e32 v124, v124, v175
	v_sub_f32_e32 v125, v125, v175
	v_sub_f32_e32 v126, v126, v175
	v_sub_f32_e32 v127, v127, v175
	v_exp_f32_e32 v120, v120
	v_exp_f32_e32 v121, v121
	v_exp_f32_e32 v122, v122
	v_exp_f32_e32 v123, v123
	v_exp_f32_e32 v124, v124
	v_exp_f32_e32 v125, v125
	v_exp_f32_e32 v126, v126
	v_exp_f32_e32 v127, v127
	v_add_f32_e32 v190, v190, v120
	v_add_f32_e32 v191, v191, v121
	v_add_f32_e32 v190, v190, v122
	v_add_f32_e32 v191, v191, v123
	v_add_f32_e32 v190, v190, v124
	v_add_f32_e32 v191, v191, v125
	v_add_f32_e32 v190, v190, v126
	v_add_f32_e32 v191, v191, v127
	v_cvt_pk_bf16_f32 v156, v120, v121
	v_cvt_pk_bf16_f32 v157, v122, v123
	v_cvt_pk_bf16_f32 v158, v124, v125
	v_cvt_pk_bf16_f32 v159, v126, v127
	v_add_f32_e32 v190, v190, v191
	v_fma_f32 v167, v167, v174, v190
	s_cbranch_vccz .Lattn_noresc_T29
	s_nop 7
	s_nop 7
	v_pk_mul_f32 v[0:1], v[0:1], v[174:175] op_sel_hi:[1,0]
	v_pk_mul_f32 v[2:3], v[2:3], v[174:175] op_sel_hi:[1,0]
	v_pk_mul_f32 v[4:5], v[4:5], v[174:175] op_sel_hi:[1,0]
	v_pk_mul_f32 v[6:7], v[6:7], v[174:175] op_sel_hi:[1,0]
	v_pk_mul_f32 v[8:9], v[8:9], v[174:175] op_sel_hi:[1,0]
	v_pk_mul_f32 v[10:11], v[10:11], v[174:175] op_sel_hi:[1,0]
	v_pk_mul_f32 v[12:13], v[12:13], v[174:175] op_sel_hi:[1,0]
	v_pk_mul_f32 v[14:15], v[14:15], v[174:175] op_sel_hi:[1,0]
	v_pk_mul_f32 v[16:17], v[16:17], v[174:175] op_sel_hi:[1,0]
	v_pk_mul_f32 v[18:19], v[18:19], v[174:175] op_sel_hi:[1,0]
	v_pk_mul_f32 v[20:21], v[20:21], v[174:175] op_sel_hi:[1,0]
	v_pk_mul_f32 v[22:23], v[22:23], v[174:175] op_sel_hi:[1,0]
	v_pk_mul_f32 v[24:25], v[24:25], v[174:175] op_sel_hi:[1,0]
	v_pk_mul_f32 v[26:27], v[26:27], v[174:175] op_sel_hi:[1,0]
	v_pk_mul_f32 v[28:29], v[28:29], v[174:175] op_sel_hi:[1,0]
	v_pk_mul_f32 v[30:31], v[30:31], v[174:175] op_sel_hi:[1,0]
	v_pk_mul_f32 v[32:33], v[32:33], v[174:175] op_sel_hi:[1,0]
	v_pk_mul_f32 v[34:35], v[34:35], v[174:175] op_sel_hi:[1,0]
	v_pk_mul_f32 v[36:37], v[36:37], v[174:175] op_sel_hi:[1,0]
	v_pk_mul_f32 v[38:39], v[38:39], v[174:175] op_sel_hi:[1,0]
	v_pk_mul_f32 v[40:41], v[40:41], v[174:175] op_sel_hi:[1,0]
	v_pk_mul_f32 v[42:43], v[42:43], v[174:175] op_sel_hi:[1,0]
	v_pk_mul_f32 v[44:45], v[44:45], v[174:175] op_sel_hi:[1,0]
	v_pk_mul_f32 v[46:47], v[46:47], v[174:175] op_sel_hi:[1,0]
	v_pk_mul_f32 v[48:49], v[48:49], v[174:175] op_sel_hi:[1,0]
	v_pk_mul_f32 v[50:51], v[50:51], v[174:175] op_sel_hi:[1,0]
	v_pk_mul_f32 v[52:53], v[52:53], v[174:175] op_sel_hi:[1,0]
	v_pk_mul_f32 v[54:55], v[54:55], v[174:175] op_sel_hi:[1,0]
	v_pk_mul_f32 v[56:57], v[56:57], v[174:175] op_sel_hi:[1,0]
	v_pk_mul_f32 v[58:59], v[58:59], v[174:175] op_sel_hi:[1,0]
	v_pk_mul_f32 v[60:61], v[60:61], v[174:175] op_sel_hi:[1,0]
	v_pk_mul_f32 v[62:63], v[62:63], v[174:175] op_sel_hi:[1,0]
	s_nop 1
